# GEMM K-loops: duplicate s_waitcnt lgkmcnt(0) at the head of each MFMA segment removed (24 sites)
# speedup vs baseline: 1.0201x; 1.0047x over previous
.LBB0_173:
	s_add_u32 s64, s62, 0x100
	s_addc_u32 s65, s63, 0
	s_add_i32 s34, 0, 0x10000
	v_add_u32_e32 v108, s34, v196
	ds_read_b128 v[96:99], v108
	ds_read_b128 v[100:103], v108 offset:1024
	ds_read_b128 v[104:107], v108 offset:2048
	ds_read_b128 v[158:161], v108 offset:3072
	s_cmp_eq_u32 s83, 28
	s_cselect_b32 s69, s57, s65
	s_cselect_b32 s68, s71, s64
	s_cselect_b32 s67, s55, s82
	s_cselect_b32 s66, s80, s81
	v_lshl_add_u64 v[108:109], s[62:63], 0, v[154:155]
	s_add_i32 m0, s44, 0xc000
	ds_read_b128 v[162:165], v207
	ds_read_b128 v[166:169], v207 offset:1024
	ds_read_b128 v[170:173], v207 offset:2048
	ds_read_b128 v[180:183], v207 offset:3072
	ds_read_b128 v[184:187], v207 offset:4096
	ds_read_b128 v[188:191], v207 offset:5120
	ds_read_b128 v[192:195], v207 offset:6144
	ds_read_b128 v[198:201], v207 offset:7168
	global_load_lds_dwordx4 v[108:109], off
	v_lshl_add_u64 v[108:109], s[62:63], 0, v[156:157]
	s_add_i32 m0, s44, 0xe000
	s_nop 0
	global_load_lds_dwordx4 v[108:109], off
	s_waitcnt lgkmcnt(8)
	s_barrier
	s_waitcnt lgkmcnt(0)
	v_mfma_f32_16x16x32_bf16 v[138:141], v[96:99], v[162:165], v[138:141]
	v_mfma_f32_16x16x32_bf16 v[60:63], v[104:107], v[162:165], v[60:63]
	v_mfma_f32_16x16x32_bf16 v[134:137], v[96:99], v[170:173], v[134:137]
	v_mfma_f32_16x16x32_bf16 v[56:59], v[104:107], v[170:173], v[56:59]
	v_mfma_f32_16x16x32_bf16 v[130:133], v[96:99], v[184:187], v[130:133]
	v_mfma_f32_16x16x32_bf16 v[52:55], v[104:107], v[184:187], v[52:55]
	v_mfma_f32_16x16x32_bf16 v[126:129], v[96:99], v[192:195], v[126:129]
	v_mfma_f32_16x16x32_bf16 v[48:51], v[104:107], v[192:195], v[48:51]
	v_mfma_f32_16x16x32_bf16 v[138:141], v[100:103], v[166:169], v[138:141]
	v_mfma_f32_16x16x32_bf16 v[60:63], v[158:161], v[166:169], v[60:63]
	v_mfma_f32_16x16x32_bf16 v[134:137], v[100:103], v[180:183], v[134:137]
	v_mfma_f32_16x16x32_bf16 v[56:59], v[158:161], v[180:183], v[56:59]
	v_mfma_f32_16x16x32_bf16 v[130:133], v[100:103], v[188:191], v[130:133]
	v_mfma_f32_16x16x32_bf16 v[52:55], v[158:161], v[188:191], v[52:55]
	v_mfma_f32_16x16x32_bf16 v[126:129], v[100:103], v[198:201], v[126:129]
	v_mfma_f32_16x16x32_bf16 v[48:51], v[158:161], v[198:201], v[48:51]
	s_barrier
	s_add_i32 s35, 0, 0x14000
	s_add_i32 s34, s34, s39
	v_add_u32_e32 v108, s35, v196
	v_lshl_add_u64 v[174:175], s[66:67], 0, v[146:147]
	s_mov_b32 m0, s34
	ds_read_b128 v[208:211], v108
	ds_read_b128 v[212:215], v108 offset:1024
	ds_read_b128 v[216:219], v108 offset:2048
	ds_read_b128 v[220:223], v108 offset:3072
	global_load_lds_dwordx4 v[174:175], off
	v_lshl_add_u64 v[224:225], s[66:67], 0, v[142:143]
	s_add_i32 m0, s34, 0x2000
	s_nop 0
	global_load_lds_dwordx4 v[224:225], off
	s_barrier
	s_waitcnt lgkmcnt(0)
	v_mfma_f32_16x16x32_bf16 v[122:125], v[208:211], v[162:165], v[122:125]
	v_mfma_f32_16x16x32_bf16 v[44:47], v[216:219], v[162:165], v[44:47]
	v_mfma_f32_16x16x32_bf16 v[114:117], v[208:211], v[170:173], v[114:117]
	v_mfma_f32_16x16x32_bf16 v[36:39], v[216:219], v[170:173], v[36:39]
	v_mfma_f32_16x16x32_bf16 v[118:121], v[208:211], v[184:187], v[118:121]
	v_mfma_f32_16x16x32_bf16 v[40:43], v[216:219], v[184:187], v[40:43]
	v_mfma_f32_16x16x32_bf16 v[108:111], v[208:211], v[192:195], v[110:113]
	v_mfma_f32_16x16x32_bf16 v[32:35], v[216:219], v[192:195], v[32:35]
	v_mfma_f32_16x16x32_bf16 v[122:125], v[212:215], v[166:169], v[122:125]
	v_mfma_f32_16x16x32_bf16 v[44:47], v[220:223], v[166:169], v[44:47]
	v_mfma_f32_16x16x32_bf16 v[114:117], v[212:215], v[180:183], v[114:117]
	v_mfma_f32_16x16x32_bf16 v[36:39], v[220:223], v[180:183], v[36:39]
	v_mfma_f32_16x16x32_bf16 v[118:121], v[212:215], v[188:191], v[118:121]
	v_mfma_f32_16x16x32_bf16 v[40:43], v[220:223], v[188:191], v[40:43]
	v_mfma_f32_16x16x32_bf16 v[108:111], v[212:215], v[198:201], v[108:111]
	v_mfma_f32_16x16x32_bf16 v[32:35], v[220:223], v[198:201], v[32:35]
	s_mov_b32 m0, s44
	v_lshl_add_u64 v[226:227], s[68:69], 0, v[148:149]
	s_barrier
	ds_read_b128 v[162:165], v207 offset:16384
	ds_read_b128 v[166:169], v207 offset:17408
	ds_read_b128 v[170:173], v207 offset:18432
	ds_read_b128 v[180:183], v207 offset:19456
	ds_read_b128 v[184:187], v207 offset:20480
	ds_read_b128 v[188:191], v207 offset:21504
	ds_read_b128 v[192:195], v207 offset:22528
	ds_read_b128 v[198:201], v207 offset:23552
	global_load_lds_dwordx4 v[226:227], off
	v_lshl_add_u64 v[228:229], s[68:69], 0, v[144:145]
	s_mov_b32 m0, s72
	s_nop 0
	global_load_lds_dwordx4 v[228:229], off
	s_barrier
	s_waitcnt lgkmcnt(0)
	v_mfma_f32_16x16x32_bf16 v[92:95], v[96:99], v[162:165], v[92:95]
	v_mfma_f32_16x16x32_bf16 v[28:31], v[104:107], v[162:165], v[28:31]
	v_mfma_f32_16x16x32_bf16 v[88:91], v[96:99], v[170:173], v[88:91]
	v_mfma_f32_16x16x32_bf16 v[24:27], v[104:107], v[170:173], v[24:27]
	v_mfma_f32_16x16x32_bf16 v[84:87], v[96:99], v[184:187], v[84:87]
	v_mfma_f32_16x16x32_bf16 v[20:23], v[104:107], v[184:187], v[20:23]
	v_mfma_f32_16x16x32_bf16 v[80:83], v[96:99], v[192:195], v[80:83]
	v_mfma_f32_16x16x32_bf16 v[16:19], v[104:107], v[192:195], v[16:19]
	v_mfma_f32_16x16x32_bf16 v[92:95], v[100:103], v[166:169], v[92:95]
	v_mfma_f32_16x16x32_bf16 v[28:31], v[158:161], v[166:169], v[28:31]
	v_mfma_f32_16x16x32_bf16 v[88:91], v[100:103], v[180:183], v[88:91]
	v_mfma_f32_16x16x32_bf16 v[24:27], v[158:161], v[180:183], v[24:27]
	v_mfma_f32_16x16x32_bf16 v[84:87], v[100:103], v[188:191], v[84:87]
	v_mfma_f32_16x16x32_bf16 v[20:23], v[158:161], v[188:191], v[20:23]
	v_mfma_f32_16x16x32_bf16 v[80:83], v[100:103], v[198:201], v[80:83]
	v_mfma_f32_16x16x32_bf16 v[16:19], v[158:161], v[198:201], v[16:19]
	s_barrier
	s_add_u32 s62, s66, 0x80000
	s_addc_u32 s63, s67, 0
	s_add_i32 s34, s35, s39
	v_lshl_add_u64 v[96:97], s[62:63], 0, v[146:147]
	s_mov_b32 m0, s34
	s_nop 0
	global_load_lds_dwordx4 v[96:97], off
	v_lshl_add_u64 v[96:97], s[62:63], 0, v[142:143]
	s_add_i32 m0, s34, 0x2000
	s_nop 0
	global_load_lds_dwordx4 v[96:97], off
	s_waitcnt vmcnt(6)
	s_barrier
	v_mfma_f32_16x16x32_bf16 v[76:79], v[208:211], v[162:165], v[76:79]
	v_mfma_f32_16x16x32_bf16 v[12:15], v[216:219], v[162:165], v[12:15]
	v_mfma_f32_16x16x32_bf16 v[68:71], v[208:211], v[170:173], v[68:71]
	v_mfma_f32_16x16x32_bf16 v[4:7], v[216:219], v[170:173], v[4:7]
	v_mfma_f32_16x16x32_bf16 v[72:75], v[208:211], v[184:187], v[72:75]
	v_mfma_f32_16x16x32_bf16 v[8:11], v[216:219], v[184:187], v[8:11]
	v_mfma_f32_16x16x32_bf16 v[64:67], v[208:211], v[192:195], v[64:67]
	v_mfma_f32_16x16x32_bf16 v[0:3], v[216:219], v[192:195], v[0:3]
	v_mfma_f32_16x16x32_bf16 v[76:79], v[212:215], v[166:169], v[76:79]
	v_mfma_f32_16x16x32_bf16 v[12:15], v[220:223], v[166:169], v[12:15]
	v_mfma_f32_16x16x32_bf16 v[68:71], v[212:215], v[180:183], v[68:71]
	v_mfma_f32_16x16x32_bf16 v[4:7], v[220:223], v[180:183], v[4:7]
	v_mfma_f32_16x16x32_bf16 v[72:75], v[212:215], v[188:191], v[72:75]
	v_mfma_f32_16x16x32_bf16 v[8:11], v[220:223], v[188:191], v[8:11]
	v_mfma_f32_16x16x32_bf16 v[64:67], v[212:215], v[198:201], v[64:67]
	v_mfma_f32_16x16x32_bf16 v[0:3], v[220:223], v[198:201], v[0:3]
	s_add_i32 s34, 0, 0x18000
	v_add_u32_e32 v112, s34, v196
	s_barrier
	ds_read_b128 v[96:99], v112
	ds_read_b128 v[100:103], v112 offset:1024
	ds_read_b128 v[104:107], v112 offset:2048
	ds_read_b128 v[158:161], v112 offset:3072
	s_add_u32 s62, s68, 0x80000
	s_addc_u32 s63, s69, 0
	s_mov_b32 m0, s73
	v_lshl_add_u64 v[112:113], s[62:63], 0, v[148:149]
	ds_read_b128 v[162:165], v207 offset:32768
	ds_read_b128 v[166:169], v207 offset:33792
	ds_read_b128 v[170:173], v207 offset:34816
	ds_read_b128 v[180:183], v207 offset:35840
	ds_read_b128 v[184:187], v207 offset:36864
	ds_read_b128 v[188:191], v207 offset:37888
	ds_read_b128 v[192:195], v207 offset:38912
	ds_read_b128 v[198:201], v207 offset:39936
	global_load_lds_dwordx4 v[112:113], off
	v_lshl_add_u64 v[112:113], s[62:63], 0, v[144:145]
	s_mov_b32 m0, s74
	s_nop 0
	global_load_lds_dwordx4 v[112:113], off
	s_waitcnt lgkmcnt(8)
	s_barrier
	s_waitcnt lgkmcnt(0)
	v_mfma_f32_16x16x32_bf16 v[138:141], v[96:99], v[162:165], v[138:141]
	v_mfma_f32_16x16x32_bf16 v[60:63], v[104:107], v[162:165], v[60:63]
	v_mfma_f32_16x16x32_bf16 v[134:137], v[96:99], v[170:173], v[134:137]
	v_mfma_f32_16x16x32_bf16 v[56:59], v[104:107], v[170:173], v[56:59]
	v_mfma_f32_16x16x32_bf16 v[130:133], v[96:99], v[184:187], v[130:133]
	v_mfma_f32_16x16x32_bf16 v[52:55], v[104:107], v[184:187], v[52:55]
	v_mfma_f32_16x16x32_bf16 v[126:129], v[96:99], v[192:195], v[126:129]
	v_mfma_f32_16x16x32_bf16 v[48:51], v[104:107], v[192:195], v[48:51]
	v_mfma_f32_16x16x32_bf16 v[138:141], v[100:103], v[166:169], v[138:141]
	v_mfma_f32_16x16x32_bf16 v[60:63], v[158:161], v[166:169], v[60:63]
	v_mfma_f32_16x16x32_bf16 v[134:137], v[100:103], v[180:183], v[134:137]
	v_mfma_f32_16x16x32_bf16 v[56:59], v[158:161], v[180:183], v[56:59]
	v_mfma_f32_16x16x32_bf16 v[130:133], v[100:103], v[188:191], v[130:133]
	v_mfma_f32_16x16x32_bf16 v[52:55], v[158:161], v[188:191], v[52:55]
	v_mfma_f32_16x16x32_bf16 v[126:129], v[100:103], v[198:201], v[126:129]
	v_mfma_f32_16x16x32_bf16 v[48:51], v[158:161], v[198:201], v[48:51]
	s_barrier
	s_add_i32 s35, 0, 0x1c000
	v_add_u32_e32 v112, s35, v196
	s_add_i32 s34, s34, s39
	ds_read_b128 v[208:211], v112
	ds_read_b128 v[212:215], v112 offset:1024
	ds_read_b128 v[216:219], v112 offset:2048
	ds_read_b128 v[220:223], v112 offset:3072
	v_lshl_add_u64 v[112:113], v[174:175], 0, s[40:41]
	s_mov_b32 m0, s34
	s_nop 0
	global_load_lds_dwordx4 v[112:113], off
	v_lshl_add_u64 v[112:113], v[224:225], 0, s[40:41]
	s_add_i32 m0, s34, 0x2000
	s_nop 0
	global_load_lds_dwordx4 v[112:113], off
	s_barrier
	s_waitcnt lgkmcnt(0)
	v_mfma_f32_16x16x32_bf16 v[122:125], v[208:211], v[162:165], v[122:125]
	v_mfma_f32_16x16x32_bf16 v[44:47], v[216:219], v[162:165], v[44:47]
	v_mfma_f32_16x16x32_bf16 v[112:115], v[208:211], v[170:173], v[114:117]
	v_mfma_f32_16x16x32_bf16 v[36:39], v[216:219], v[170:173], v[36:39]
	v_mfma_f32_16x16x32_bf16 v[118:121], v[208:211], v[184:187], v[118:121]
	v_mfma_f32_16x16x32_bf16 v[40:43], v[216:219], v[184:187], v[40:43]
	v_mfma_f32_16x16x32_bf16 v[108:111], v[208:211], v[192:195], v[108:111]
	v_mfma_f32_16x16x32_bf16 v[32:35], v[216:219], v[192:195], v[32:35]
	v_mfma_f32_16x16x32_bf16 v[122:125], v[212:215], v[166:169], v[122:125]
	v_mfma_f32_16x16x32_bf16 v[44:47], v[220:223], v[166:169], v[44:47]
	v_mfma_f32_16x16x32_bf16 v[114:117], v[212:215], v[180:183], v[112:115]
	v_mfma_f32_16x16x32_bf16 v[36:39], v[220:223], v[180:183], v[36:39]
	v_mfma_f32_16x16x32_bf16 v[118:121], v[212:215], v[188:191], v[118:121]
	v_mfma_f32_16x16x32_bf16 v[40:43], v[220:223], v[188:191], v[40:43]
	v_mfma_f32_16x16x32_bf16 v[110:113], v[212:215], v[198:201], v[108:111]
	v_mfma_f32_16x16x32_bf16 v[32:35], v[220:223], v[198:201], v[32:35]
	s_mov_b32 m0, s76
	v_lshl_add_u64 v[108:109], v[226:227], 0, s[40:41]
	s_barrier
	ds_read_b128 v[162:165], v207 offset:49152
	ds_read_b128 v[166:169], v207 offset:50176
	ds_read_b128 v[170:173], v207 offset:51200
	ds_read_b128 v[180:183], v207 offset:52224
	ds_read_b128 v[184:187], v207 offset:53248
	ds_read_b128 v[188:191], v207 offset:54272
	ds_read_b128 v[192:195], v207 offset:55296
	ds_read_b128 v[198:201], v207 offset:56320
	global_load_lds_dwordx4 v[108:109], off
	v_lshl_add_u64 v[108:109], v[228:229], 0, s[40:41]
	s_mov_b32 m0, s77
	s_nop 0
	global_load_lds_dwordx4 v[108:109], off
	s_barrier
	s_waitcnt lgkmcnt(0)
	v_mfma_f32_16x16x32_bf16 v[92:95], v[96:99], v[162:165], v[92:95]
	v_mfma_f32_16x16x32_bf16 v[28:31], v[104:107], v[162:165], v[28:31]
	v_mfma_f32_16x16x32_bf16 v[88:91], v[96:99], v[170:173], v[88:91]
	v_mfma_f32_16x16x32_bf16 v[24:27], v[104:107], v[170:173], v[24:27]
	v_mfma_f32_16x16x32_bf16 v[84:87], v[96:99], v[184:187], v[84:87]
	v_mfma_f32_16x16x32_bf16 v[20:23], v[104:107], v[184:187], v[20:23]
	v_mfma_f32_16x16x32_bf16 v[80:83], v[96:99], v[192:195], v[80:83]
	v_mfma_f32_16x16x32_bf16 v[16:19], v[104:107], v[192:195], v[16:19]
	v_mfma_f32_16x16x32_bf16 v[92:95], v[100:103], v[166:169], v[92:95]
	v_mfma_f32_16x16x32_bf16 v[28:31], v[158:161], v[166:169], v[28:31]
	v_mfma_f32_16x16x32_bf16 v[88:91], v[100:103], v[180:183], v[88:91]
	v_mfma_f32_16x16x32_bf16 v[24:27], v[158:161], v[180:183], v[24:27]
	v_mfma_f32_16x16x32_bf16 v[84:87], v[100:103], v[188:191], v[84:87]
	v_mfma_f32_16x16x32_bf16 v[20:23], v[158:161], v[188:191], v[20:23]
	v_mfma_f32_16x16x32_bf16 v[80:83], v[100:103], v[198:201], v[80:83]
	v_mfma_f32_16x16x32_bf16 v[16:19], v[158:161], v[198:201], v[16:19]
	s_barrier
	s_add_u32 s62, s66, 0x80080
	s_addc_u32 s63, s67, 0
	s_add_i32 s34, s35, s39
	v_lshl_add_u64 v[96:97], s[62:63], 0, v[146:147]
	s_mov_b32 m0, s34
	s_nop 0
	global_load_lds_dwordx4 v[96:97], off
	v_lshl_add_u64 v[96:97], s[62:63], 0, v[142:143]
	s_add_i32 m0, s34, 0x2000
	s_nop 0
	global_load_lds_dwordx4 v[96:97], off
	s_waitcnt vmcnt(6)
	s_barrier
	v_mfma_f32_16x16x32_bf16 v[76:79], v[208:211], v[162:165], v[76:79]
	v_mfma_f32_16x16x32_bf16 v[12:15], v[216:219], v[162:165], v[12:15]
	v_mfma_f32_16x16x32_bf16 v[68:71], v[208:211], v[170:173], v[68:71]
	v_mfma_f32_16x16x32_bf16 v[4:7], v[216:219], v[170:173], v[4:7]
	v_mfma_f32_16x16x32_bf16 v[72:75], v[208:211], v[184:187], v[72:75]
	v_mfma_f32_16x16x32_bf16 v[8:11], v[216:219], v[184:187], v[8:11]
	v_mfma_f32_16x16x32_bf16 v[64:67], v[208:211], v[192:195], v[64:67]
	v_mfma_f32_16x16x32_bf16 v[0:3], v[216:219], v[192:195], v[0:3]
	v_mfma_f32_16x16x32_bf16 v[76:79], v[212:215], v[166:169], v[76:79]
	v_mfma_f32_16x16x32_bf16 v[12:15], v[220:223], v[166:169], v[12:15]
	v_mfma_f32_16x16x32_bf16 v[68:71], v[212:215], v[180:183], v[68:71]
	v_mfma_f32_16x16x32_bf16 v[4:7], v[220:223], v[180:183], v[4:7]
	v_mfma_f32_16x16x32_bf16 v[72:75], v[212:215], v[188:191], v[72:75]
	v_mfma_f32_16x16x32_bf16 v[8:11], v[220:223], v[188:191], v[8:11]
	v_mfma_f32_16x16x32_bf16 v[64:67], v[212:215], v[198:201], v[64:67]
	v_mfma_f32_16x16x32_bf16 v[0:3], v[220:223], v[198:201], v[0:3]
	s_add_i32 s83, s83, 2
	s_add_u32 s81, s81, 0x100
	s_addc_u32 s82, s82, 0
	s_cmp_gt_u32 s83, 29
	s_mov_b64 s[62:63], s[64:65]
	s_barrier
	s_cbranch_scc0 .LBB0_173
	v_lshl_or_b32 v158, s70, 7, v150
	v_ashrrev_i32_e32 v159, 31, v158
	v_lshlrev_b64 v[96:97], 2, v[158:159]
	v_lshl_add_u64 v[98:99], s[30:31], 0, v[96:97]
	v_lshl_add_u64 v[100:101], s[46:47], 0, v[96:97]
	v_lshl_add_u64 v[102:103], s[24:25], 0, v[96:97]
	global_load_dwordx4 v[160:163], v[98:99], off
	global_load_dwordx4 v[170:173], v[100:101], off
	v_lshl_add_u64 v[98:99], s[42:43], 0, v[96:97]
	v_lshl_add_u64 v[100:101], s[48:49], 0, v[96:97]
	global_load_dwordx4 v[104:107], v[102:103], off
	global_load_dwordx4 v[164:167], v[98:99], off
	global_load_dwordx4 v[208:211], v[100:101], off
	v_lshl_add_u64 v[100:101], s[50:51], 0, v[96:97]
	global_load_dwordx4 v[212:215], v[100:101], off
	v_lshl_add_u64 v[98:99], s[26:27], 0, v[96:97]
	global_load_dwordx4 v[198:201], v[98:99], off
	v_lshl_add_u64 v[96:97], s[52:53], 0, v[96:97]
	global_load_dwordx4 v[216:219], v[96:97], off
	v_mov_b32_e32 v96, v177
	v_mov_b32_e32 v97, v177
	s_mov_b32 s62, 0xbf317218
	v_mov_b32_dpp v96, v126 row_ror:1 row_mask:0xf bank_mask:0xf
	v_mov_b32_dpp v97, v127 row_ror:1 row_mask:0xf bank_mask:0xf
	s_mov_b32 s34, 0xbfb8aa3b
	v_mov_b32_e32 v100, v177
	v_mov_b32_e32 v101, v177
	v_mov_b32_e32 v224, v177
	v_mov_b32_e32 v225, v177
	v_mov_b32_dpp v100, v138 row_ror:15 row_mask:0xf bank_mask:0xf
	v_mov_b32_dpp v101, v139 row_ror:15 row_mask:0xf bank_mask:0xf
	v_mov_b32_e32 v220, v177
	v_mov_b32_e32 v221, v177
	v_mov_b32_dpp v224, v112 row_ror:1 row_mask:0xf bank_mask:0xf
	v_mov_b32_dpp v225, v113 row_ror:1 row_mask:0xf bank_mask:0xf
	v_mov_b32_dpp v220, v128 row_ror:1 row_mask:0xf bank_mask:0xf
	v_mov_b32_dpp v221, v129 row_ror:1 row_mask:0xf bank_mask:0xf
	v_mov_b32_e32 v222, v177
	v_mov_b32_e32 v223, v177
	v_mov_b32_e32 v108, v177
	v_mov_b32_e32 v180, v177
	v_mov_b32_e32 v109, v177
	v_mov_b32_e32 v181, v177
	v_mov_b32_dpp v222, v140 row_ror:15 row_mask:0xf bank_mask:0xf
	v_mov_b32_dpp v223, v141 row_ror:15 row_mask:0xf bank_mask:0xf
	v_mov_b32_dpp v108, v110 row_ror:1 row_mask:0xf bank_mask:0xf
	v_mov_b32_dpp v180, v122 row_ror:15 row_mask:0xf bank_mask:0xf
	v_mov_b32_dpp v109, v111 row_ror:1 row_mask:0xf bank_mask:0xf
	v_mov_b32_dpp v181, v123 row_ror:15 row_mask:0xf bank_mask:0xf
	v_mov_b32_e32 v226, v177
	v_mov_b32_e32 v227, v177
	v_cmp_gt_i32_e32 vcc, 15, v151
	v_mov_b32_dpp v226, v124 row_ror:15 row_mask:0xf bank_mask:0xf
	v_mov_b32_dpp v227, v125 row_ror:15 row_mask:0xf bank_mask:0xf
	s_mov_b64 s[68:69], -1
	s_waitcnt vmcnt(0)
	v_pk_mul_f32 v[192:193], v[160:161], s[62:63] op_sel_hi:[1,0]
	v_pk_mul_f32 v[168:169], v[172:173], s[34:35] op_sel_hi:[1,0]
	v_pk_mul_f32 v[228:229], v[126:127], v[192:193]
	v_pk_mul_f32 v[194:195], v[162:163], s[62:63] op_sel_hi:[1,0]
	v_pk_mul_f32 v[186:187], v[104:105], s[62:63] op_sel_hi:[1,0]
	v_pk_mul_f32 v[188:189], v[166:167], s[62:63] op_sel_hi:[1,0]
	v_pk_mul_f32 v[172:173], v[210:211], s[34:35] op_sel_hi:[1,0]
	v_pk_mul_f32 v[96:97], v[186:187], v[96:97]
	v_pk_mul_f32 v[166:167], v[214:215], s[34:35] op_sel_hi:[1,0]
	v_pk_mul_f32 v[210:211], v[134:135], v[192:193]
	v_pk_mul_f32 v[214:215], v[130:131], v[192:193]
	v_pk_mul_f32 v[182:183], v[164:165], s[62:63] op_sel_hi:[1,0]
	v_pk_fma_f32 v[96:97], v[138:139], v[192:193], v[96:97]
	v_pk_fma_f32 v[210:211], v[138:139], v[186:187], v[210:211]
	v_pk_fma_f32 v[214:215], v[134:135], v[186:187], v[214:215]
	v_pk_fma_f32 v[228:229], v[130:131], v[186:187], v[228:229]
	v_pk_fma_f32 v[96:97], v[134:135], v[182:183], v[96:97]
	v_pk_fma_f32 v[210:211], v[130:131], v[182:183], v[210:211]
	v_pk_fma_f32 v[214:215], v[126:127], v[182:183], v[214:215]
	v_pk_fma_f32 v[100:101], v[182:183], v[100:101], v[228:229]
	v_pk_mul_f32 v[190:191], v[106:107], s[62:63] op_sel_hi:[1,0]
	v_pk_mul_f32 v[174:175], v[198:199], s[62:63] op_sel_hi:[1,0]
	v_pk_fma_f32 v[96:97], v[198:199], s[62:63], v[96:97] op_sel_hi:[1,0,1]
	v_pk_fma_f32 v[210:211], v[198:199], s[62:63], v[210:211] op_sel_hi:[1,0,1]
	v_pk_fma_f32 v[214:215], v[198:199], s[62:63], v[214:215] op_sel_hi:[1,0,1]
	v_pk_fma_f32 v[100:101], v[198:199], s[62:63], v[100:101] op_sel_hi:[1,0,1]
	v_pk_mul_f32 v[198:199], v[168:169], v[224:225]
	v_pk_mul_f32 v[164:165], v[170:171], s[34:35] op_sel_hi:[1,0]
	v_pk_mul_f32 v[170:171], v[208:209], s[34:35] op_sel_hi:[1,0]
	v_pk_mul_f32 v[162:163], v[212:213], s[34:35] op_sel_hi:[1,0]
	v_pk_mul_f32 v[104:105], v[190:191], v[220:221]
	v_pk_mul_f32 v[208:209], v[136:137], v[194:195]
	v_pk_mul_f32 v[212:213], v[132:133], v[194:195]
	v_pk_mul_f32 v[220:221], v[128:129], v[194:195]
	v_pk_fma_f32 v[198:199], v[124:125], v[172:173], v[198:199]
	v_pk_fma_f32 v[104:105], v[140:141], v[194:195], v[104:105]
	v_pk_fma_f32 v[208:209], v[140:141], v[190:191], v[208:209]
	v_pk_fma_f32 v[212:213], v[136:137], v[190:191], v[212:213]
	v_pk_fma_f32 v[220:221], v[132:133], v[190:191], v[220:221]
	v_pk_fma_f32 v[198:199], v[116:117], v[166:167], v[198:199]
	v_pk_mul_f32 v[232:233], v[110:111], v[170:171]
	v_pk_fma_f32 v[104:105], v[136:137], v[188:189], v[104:105]
	v_pk_fma_f32 v[208:209], v[132:133], v[188:189], v[208:209]
	v_pk_fma_f32 v[212:213], v[128:129], v[188:189], v[212:213]
	v_pk_fma_f32 v[220:221], v[188:189], v[222:223], v[220:221]
	v_pk_fma_f32 v[198:199], v[218:219], s[34:35], v[198:199] op_sel_hi:[1,0,1]
	v_pk_fma_f32 v[232:233], v[118:119], v[164:165], v[232:233]
	v_pk_mul_f32 v[184:185], v[200:201], s[62:63] op_sel_hi:[1,0]
	v_pk_fma_f32 v[104:105], v[200:201], s[62:63], v[104:105] op_sel_hi:[1,0,1]
	v_pk_fma_f32 v[208:209], v[200:201], s[62:63], v[208:209] op_sel_hi:[1,0,1]
	v_pk_fma_f32 v[212:213], v[200:201], s[62:63], v[212:213] op_sel_hi:[1,0,1]
	v_pk_fma_f32 v[200:201], v[200:201], s[62:63], v[220:221] op_sel_hi:[1,0,1]
	v_pk_mul_f32 v[108:109], v[164:165], v[108:109]
	v_pk_mul_f32 v[220:221], v[116:117], v[172:173]
	v_pk_mul_f32 v[222:223], v[114:115], v[170:171]
	v_pk_fma_f32 v[180:181], v[162:163], v[180:181], v[232:233]
	v_exp_f32_e32 v232, v198
	v_exp_f32_e32 v233, v199
	v_pk_fma_f32 v[108:109], v[122:123], v[170:171], v[108:109]
	v_pk_fma_f32 v[220:221], v[124:125], v[168:169], v[220:221]
	v_pk_fma_f32 v[222:223], v[122:123], v[164:165], v[222:223]
	v_pk_mul_f32 v[228:229], v[118:119], v[170:171]
	v_pk_fma_f32 v[108:109], v[114:115], v[162:163], v[108:109]
	v_pk_fma_f32 v[220:221], v[120:121], v[166:167], v[220:221]
	v_pk_fma_f32 v[222:223], v[118:119], v[162:163], v[222:223]
	v_pk_fma_f32 v[228:229], v[114:115], v[164:165], v[228:229]
	v_pk_mul_f32 v[230:231], v[112:113], v[172:173]
	v_pk_fma_f32 v[108:109], v[216:217], s[34:35], v[108:109] op_sel_hi:[1,0,1]
	v_pk_fma_f32 v[220:221], v[218:219], s[34:35], v[220:221] op_sel_hi:[1,0,1]
	v_pk_fma_f32 v[222:223], v[216:217], s[34:35], v[222:223] op_sel_hi:[1,0,1]
	v_pk_fma_f32 v[228:229], v[110:111], v[162:163], v[228:229]
	v_pk_fma_f32 v[230:231], v[120:121], v[168:169], v[230:231]
	v_pk_mul_f32 v[106:107], v[216:217], s[34:35] op_sel_hi:[1,0]
	v_pk_fma_f32 v[228:229], v[216:217], s[34:35], v[228:229] op_sel_hi:[1,0,1]
	v_pk_fma_f32 v[226:227], v[166:167], v[226:227], v[230:231]
	v_exp_f32_e32 v230, v108
	v_exp_f32_e32 v231, v109
	v_pk_fma_f32 v[180:181], v[216:217], s[34:35], v[180:181] op_sel_hi:[1,0,1]
	v_pk_add_f32 v[216:217], v[232:233], 1.0 op_sel_hi:[1,0]
	v_pk_mul_f32 v[104:105], v[104:105], v[198:199]
	v_pk_mul_f32 v[96:97], v[96:97], v[108:109]
	v_exp_f32_e32 v108, v222
	v_exp_f32_e32 v198, v220
	v_exp_f32_e32 v199, v221
	v_exp_f32_e32 v109, v223
	v_pk_mul_f32 v[224:225], v[120:121], v[172:173]
	v_rcp_f32_e32 v216, v216
	v_rcp_f32_e32 v217, v217
	v_pk_fma_f32 v[224:225], v[116:117], v[168:169], v[224:225]
	v_pk_add_f32 v[198:199], v[198:199], 1.0 op_sel_hi:[1,0]
	v_pk_fma_f32 v[224:225], v[112:113], v[166:167], v[224:225]
	v_pk_add_f32 v[108:109], v[108:109], 1.0 op_sel_hi:[1,0]
	v_pk_fma_f32 v[224:225], v[218:219], s[34:35], v[224:225] op_sel_hi:[1,0,1]
	v_pk_mul_f32 v[104:105], v[104:105], v[216:217]
	v_rcp_f32_e32 v108, v108
	v_rcp_f32_e32 v109, v109
	v_rcp_f32_e32 v198, v198
	v_rcp_f32_e32 v199, v199
	v_pk_mul_f32 v[208:209], v[208:209], v[220:221]
	v_exp_f32_e32 v216, v228
	v_exp_f32_e32 v220, v224
	v_exp_f32_e32 v221, v225
	v_exp_f32_e32 v217, v229
	v_pk_mul_f32 v[210:211], v[210:211], v[222:223]
	v_pk_mul_f32 v[160:161], v[218:219], s[34:35] op_sel_hi:[1,0]
	v_pk_fma_f32 v[218:219], v[218:219], s[34:35], v[226:227] op_sel_hi:[1,0,1]
	v_pk_mul_f32 v[198:199], v[208:209], v[198:199]
	v_pk_mul_f32 v[208:209], v[210:211], v[108:109]
	v_pk_add_f32 v[108:109], v[220:221], 1.0 op_sel_hi:[1,0]
	v_pk_add_f32 v[210:211], v[216:217], 1.0 op_sel_hi:[1,0]
	v_rcp_f32_e32 v108, v108
	v_rcp_f32_e32 v210, v210
	v_rcp_f32_e32 v211, v211
	v_rcp_f32_e32 v109, v109
	v_exp_f32_e32 v216, v180
	v_exp_f32_e32 v220, v218
	v_exp_f32_e32 v221, v219
	v_exp_f32_e32 v217, v181
	v_pk_add_f32 v[226:227], v[230:231], 1.0 op_sel_hi:[1,0]
	v_pk_mul_f32 v[212:213], v[212:213], v[224:225]
	v_pk_mul_f32 v[214:215], v[214:215], v[228:229]
	v_rcp_f32_e32 v226, v226
	v_rcp_f32_e32 v227, v227
	v_pk_mul_f32 v[212:213], v[212:213], v[108:109]
	v_pk_mul_f32 v[210:211], v[214:215], v[210:211]
	v_pk_add_f32 v[108:109], v[220:221], 1.0 op_sel_hi:[1,0]
	v_pk_add_f32 v[214:215], v[216:217], 1.0 op_sel_hi:[1,0]
	v_rcp_f32_e32 v108, v108
	v_rcp_f32_e32 v214, v214
	v_rcp_f32_e32 v109, v109
	v_rcp_f32_e32 v215, v215
	v_pk_mul_f32 v[96:97], v[96:97], v[226:227]
	v_pk_mul_f32 v[200:201], v[200:201], v[218:219]
	v_pk_mul_f32 v[100:101], v[100:101], v[180:181]
	v_pk_mul_f32 v[180:181], v[200:201], v[108:109]
	v_pk_mul_f32 v[200:201], v[100:101], v[214:215]
	v_cvt_pk_bf16_f32 v108, v96, v97
	v_cvt_pk_bf16_f32 v109, v104, v105
	v_cvt_pk_bf16_f32 v104, v208, v209
	v_cvt_pk_bf16_f32 v105, v198, v199
	v_cvt_pk_bf16_f32 v100, v210, v211
	v_cvt_pk_bf16_f32 v101, v212, v213
	s_nop 0
	v_cvt_pk_bf16_f32 v96, v200, v201
	v_cvt_pk_bf16_f32 v97, v180, v181
	s_and_saveexec_b64 s[62:63], vcc
	v_cmp_eq_u32_e32 vcc, 0, v151
	s_orn2_b64 s[68:69], vcc, exec
	s_or_b64 exec, exec, s[62:63]
	s_lshl_b32 s34, s79, 2
	s_lshl_b32 s62, s70, 8
	s_add_i32 s64, s34, s38
	s_ashr_i32 s63, s62, 31
	v_lshlrev_b32_e32 v176, 2, v150
	s_mov_b64 s[66:67], exec
	s_and_b64 s[68:69], s[66:67], s[68:69]
	v_mov_b32_e32 v198, 0xbf1f24be
	s_mov_b64 exec, s[68:69]
	s_cbranch_execz .LBB0_178
	s_ashr_i32 s65, s64, 31
	s_lshl_b64 s[68:69], s[64:65], 2
	v_or_b32_e32 v178, s68, v152
	v_mov_b64_e32 v[180:181], s[4:5]
	s_mov_b32 s29, 0xb000
	v_mad_u64_u32 v[180:181], s[70:71], v178, s29, v[180:181]
	v_mad_i32_i24 v181, s69, v204, v181
	v_lshl_add_u64 v[180:181], s[62:63], 2, v[180:181]
	v_lshl_add_u64 v[180:181], v[180:181], 0, v[176:177]
	v_cndmask_b32_e64 v133, v133, v141, s[8:9]
	v_cndmask_b32_e64 v132, v132, v140, s[8:9]
	v_cndmask_b32_e64 v131, v131, v139, s[8:9]
	v_cndmask_b32_e64 v130, v130, v138, s[8:9]
	v_cndmask_b32_e64 v118, v118, v122, s[8:9]
	v_cndmask_b32_e64 v121, v121, v125, s[8:9]
	v_cndmask_b32_e64 v120, v120, v124, s[8:9]
	v_cndmask_b32_e64 v119, v119, v123, s[8:9]
	global_store_dwordx4 v[180:181], v[130:133], off
	global_store_dwordx4 v[180:181], v[118:121], off offset:512
	v_cndmask_b32_e64 v125, v129, v137, s[8:9]
	v_cndmask_b32_e64 v124, v128, v136, s[8:9]
	v_add_co_u32_e32 v118, vcc, s29, v180
	v_cndmask_b32_e64 v123, v127, v135, s[8:9]
	v_cndmask_b32_e64 v122, v126, v134, s[8:9]
	v_addc_co_u32_e32 v119, vcc, 0, v181, vcc
	v_cndmask_b32_e64 v113, v113, v117, s[8:9]
	v_cndmask_b32_e64 v112, v112, v116, s[8:9]
	v_cndmask_b32_e64 v111, v111, v115, s[8:9]
	v_cndmask_b32_e64 v110, v110, v114, s[8:9]
	global_store_dwordx4 v[118:119], v[122:125], off
	global_store_dwordx4 v[118:119], v[110:113], off offset:512

.LBB0_264:
	s_add_i32 s61, s24, 2
	s_add_u32 s26, s8, 0x80
	s_addc_u32 s25, s9, 0
	s_add_i32 s29, 0, 0x10000
	v_add_u32_e32 v140, s29, v193
	ds_read_b128 v[128:131], v140
	ds_read_b128 v[132:135], v140 offset:1024
	ds_read_b128 v[136:139], v140 offset:2048
	ds_read_b128 v[140:143], v140 offset:3072
	s_cmp_eq_u32 s47, s24
	s_cselect_b32 s24, s20, s26
	s_cselect_b32 s25, s21, s25
	s_cselect_b32 s27, s11, s60
	s_cselect_b32 s26, s10, s59
	v_lshl_add_u64 v[180:181], s[8:9], 0, v[174:175]
	s_add_i32 m0, s33, 0xc000
	ds_read_b128 v[144:147], v195
	ds_read_b128 v[148:151], v195 offset:1024
	ds_read_b128 v[152:155], v195 offset:2048
	ds_read_b128 v[156:159], v195 offset:3072
	ds_read_b128 v[160:163], v195 offset:4096
	ds_read_b128 v[164:167], v195 offset:5120
	ds_read_b128 v[184:187], v195 offset:6144
	ds_read_b128 v[188:191], v195 offset:7168
	global_load_lds_dwordx4 v[180:181], off
	v_lshl_add_u64 v[180:181], s[8:9], 0, v[182:183]
	s_add_i32 m0, s33, 0xe000
	s_nop 0
	global_load_lds_dwordx4 v[180:181], off
	s_waitcnt lgkmcnt(8)
	s_barrier
	s_waitcnt lgkmcnt(0)
	v_mfma_f32_16x16x32_bf16 v[124:127], v[128:131], v[144:147], v[124:127]
	v_mfma_f32_16x16x32_bf16 v[120:123], v[136:139], v[144:147], v[120:123]
	v_mfma_f32_16x16x32_bf16 v[108:111], v[128:131], v[152:155], v[108:111]
	v_mfma_f32_16x16x32_bf16 v[104:107], v[136:139], v[152:155], v[104:107]
	v_mfma_f32_16x16x32_bf16 v[92:95], v[128:131], v[160:163], v[92:95]
	v_mfma_f32_16x16x32_bf16 v[88:91], v[136:139], v[160:163], v[88:91]
	v_mfma_f32_16x16x32_bf16 v[76:79], v[128:131], v[184:187], v[76:79]
	v_mfma_f32_16x16x32_bf16 v[72:75], v[136:139], v[184:187], v[72:75]
	v_mfma_f32_16x16x32_bf16 v[124:127], v[132:135], v[148:151], v[124:127]
	v_mfma_f32_16x16x32_bf16 v[120:123], v[140:143], v[148:151], v[120:123]
	v_mfma_f32_16x16x32_bf16 v[108:111], v[132:135], v[156:159], v[108:111]
	v_mfma_f32_16x16x32_bf16 v[104:107], v[140:143], v[156:159], v[104:107]
	v_mfma_f32_16x16x32_bf16 v[92:95], v[132:135], v[164:167], v[92:95]
	v_mfma_f32_16x16x32_bf16 v[88:91], v[140:143], v[164:167], v[88:91]
	v_mfma_f32_16x16x32_bf16 v[76:79], v[132:135], v[188:191], v[76:79]
	v_mfma_f32_16x16x32_bf16 v[72:75], v[140:143], v[188:191], v[72:75]
	s_barrier
	s_add_i32 s34, 0, 0x14000
	s_add_i32 s29, s29, s31
	v_add_u32_e32 v178, s34, v193
	v_lshl_add_u64 v[180:181], s[26:27], 0, v[176:177]
	s_mov_b32 m0, s29
	ds_read_b128 v[196:199], v178
	ds_read_b128 v[208:211], v178 offset:1024
	ds_read_b128 v[212:215], v178 offset:2048
	ds_read_b128 v[216:219], v178 offset:3072
	global_load_lds_dwordx4 v[180:181], off
	v_lshl_add_u64 v[200:201], s[26:27], 0, v[168:169]
	s_add_i32 m0, s29, 0x2000
	s_nop 0
	global_load_lds_dwordx4 v[200:201], off
	s_barrier
	s_waitcnt lgkmcnt(0)
	v_mfma_f32_16x16x32_bf16 v[116:119], v[196:199], v[144:147], v[116:119]
	v_mfma_f32_16x16x32_bf16 v[112:115], v[212:215], v[144:147], v[112:115]
	v_mfma_f32_16x16x32_bf16 v[100:103], v[196:199], v[152:155], v[100:103]
	v_mfma_f32_16x16x32_bf16 v[96:99], v[212:215], v[152:155], v[96:99]
	v_mfma_f32_16x16x32_bf16 v[84:87], v[196:199], v[160:163], v[84:87]
	v_mfma_f32_16x16x32_bf16 v[80:83], v[212:215], v[160:163], v[80:83]
	v_mfma_f32_16x16x32_bf16 v[68:71], v[196:199], v[184:187], v[68:71]
	v_mfma_f32_16x16x32_bf16 v[64:67], v[212:215], v[184:187], v[64:67]
	v_mfma_f32_16x16x32_bf16 v[116:119], v[208:211], v[148:151], v[116:119]
	v_mfma_f32_16x16x32_bf16 v[112:115], v[216:219], v[148:151], v[112:115]
	v_mfma_f32_16x16x32_bf16 v[100:103], v[208:211], v[156:159], v[100:103]
	v_mfma_f32_16x16x32_bf16 v[96:99], v[216:219], v[156:159], v[96:99]
	v_mfma_f32_16x16x32_bf16 v[84:87], v[208:211], v[164:167], v[84:87]
	v_mfma_f32_16x16x32_bf16 v[80:83], v[216:219], v[164:167], v[80:83]
	v_mfma_f32_16x16x32_bf16 v[68:71], v[208:211], v[188:191], v[68:71]
	v_mfma_f32_16x16x32_bf16 v[64:67], v[216:219], v[188:191], v[64:67]
	s_mov_b32 m0, s33
	v_lshl_add_u64 v[220:221], s[24:25], 0, v[172:173]
	s_barrier
	ds_read_b128 v[144:147], v195 offset:16384
	ds_read_b128 v[148:151], v195 offset:17408
	ds_read_b128 v[152:155], v195 offset:18432
	ds_read_b128 v[156:159], v195 offset:19456
	ds_read_b128 v[160:163], v195 offset:20480
	ds_read_b128 v[164:167], v195 offset:21504
	ds_read_b128 v[184:187], v195 offset:22528
	ds_read_b128 v[188:191], v195 offset:23552
	global_load_lds_dwordx4 v[220:221], off
	v_lshl_add_u64 v[222:223], s[24:25], 0, v[170:171]
	s_mov_b32 m0, s37
	s_nop 0
	global_load_lds_dwordx4 v[222:223], off
	s_barrier
	s_waitcnt lgkmcnt(0)
	v_mfma_f32_16x16x32_bf16 v[60:63], v[128:131], v[144:147], v[60:63]
	v_mfma_f32_16x16x32_bf16 v[56:59], v[136:139], v[144:147], v[56:59]
	v_mfma_f32_16x16x32_bf16 v[44:47], v[128:131], v[152:155], v[44:47]
	v_mfma_f32_16x16x32_bf16 v[40:43], v[136:139], v[152:155], v[40:43]
	v_mfma_f32_16x16x32_bf16 v[28:31], v[128:131], v[160:163], v[28:31]
	v_mfma_f32_16x16x32_bf16 v[24:27], v[136:139], v[160:163], v[24:27]
	v_mfma_f32_16x16x32_bf16 v[12:15], v[128:131], v[184:187], v[12:15]
	v_mfma_f32_16x16x32_bf16 v[8:11], v[136:139], v[184:187], v[8:11]
	v_mfma_f32_16x16x32_bf16 v[60:63], v[132:135], v[148:151], v[60:63]
	v_mfma_f32_16x16x32_bf16 v[56:59], v[140:143], v[148:151], v[56:59]
	v_mfma_f32_16x16x32_bf16 v[44:47], v[132:135], v[156:159], v[44:47]
	v_mfma_f32_16x16x32_bf16 v[40:43], v[140:143], v[156:159], v[40:43]
	v_mfma_f32_16x16x32_bf16 v[28:31], v[132:135], v[164:167], v[28:31]
	v_mfma_f32_16x16x32_bf16 v[24:27], v[140:143], v[164:167], v[24:27]
	v_mfma_f32_16x16x32_bf16 v[12:15], v[132:135], v[188:191], v[12:15]
	v_mfma_f32_16x16x32_bf16 v[8:11], v[140:143], v[188:191], v[8:11]
	s_barrier
	s_add_u32 s26, s26, s44
	s_addc_u32 s27, s27, 0
	s_add_i32 s29, s34, s31
	v_lshl_add_u64 v[224:225], s[26:27], 0, v[176:177]
	s_mov_b32 m0, s29
	v_lshl_add_u64 v[226:227], s[26:27], 0, v[168:169]
	global_load_lds_dwordx4 v[224:225], off
	s_add_i32 m0, s29, 0x2000
	s_nop 0
	global_load_lds_dwordx4 v[226:227], off
	s_waitcnt vmcnt(6)
	s_barrier
	v_mfma_f32_16x16x32_bf16 v[52:55], v[196:199], v[144:147], v[52:55]
	v_mfma_f32_16x16x32_bf16 v[48:51], v[212:215], v[144:147], v[48:51]
	v_mfma_f32_16x16x32_bf16 v[36:39], v[196:199], v[152:155], v[36:39]
	v_mfma_f32_16x16x32_bf16 v[32:35], v[212:215], v[152:155], v[32:35]
	v_mfma_f32_16x16x32_bf16 v[20:23], v[196:199], v[160:163], v[20:23]
	v_mfma_f32_16x16x32_bf16 v[16:19], v[212:215], v[160:163], v[16:19]
	v_mfma_f32_16x16x32_bf16 v[4:7], v[196:199], v[184:187], v[4:7]
	v_mfma_f32_16x16x32_bf16 v[0:3], v[212:215], v[184:187], v[0:3]
	v_mfma_f32_16x16x32_bf16 v[52:55], v[208:211], v[148:151], v[52:55]
	v_mfma_f32_16x16x32_bf16 v[48:51], v[216:219], v[148:151], v[48:51]
	v_mfma_f32_16x16x32_bf16 v[36:39], v[208:211], v[156:159], v[36:39]
	v_mfma_f32_16x16x32_bf16 v[32:35], v[216:219], v[156:159], v[32:35]
	v_mfma_f32_16x16x32_bf16 v[20:23], v[208:211], v[164:167], v[20:23]
	v_mfma_f32_16x16x32_bf16 v[16:19], v[216:219], v[164:167], v[16:19]
	v_mfma_f32_16x16x32_bf16 v[4:7], v[208:211], v[188:191], v[4:7]
	v_mfma_f32_16x16x32_bf16 v[0:3], v[216:219], v[188:191], v[0:3]
	s_add_i32 s26, 0, 0x18000
	v_add_u32_e32 v140, s26, v193
	s_barrier
	ds_read_b128 v[128:131], v140
	ds_read_b128 v[132:135], v140 offset:1024
	ds_read_b128 v[136:139], v140 offset:2048
	ds_read_b128 v[140:143], v140 offset:3072
	s_add_u32 s24, s24, s44
	s_addc_u32 s25, s25, 0
	s_mov_b32 m0, s38
	v_lshl_add_u64 v[196:197], s[24:25], 0, v[172:173]
	ds_read_b128 v[144:147], v195 offset:32768
	ds_read_b128 v[148:151], v195 offset:33792
	ds_read_b128 v[152:155], v195 offset:34816
	ds_read_b128 v[156:159], v195 offset:35840
	ds_read_b128 v[160:163], v195 offset:36864
	ds_read_b128 v[164:167], v195 offset:37888
	ds_read_b128 v[184:187], v195 offset:38912
	ds_read_b128 v[188:191], v195 offset:39936
	global_load_lds_dwordx4 v[196:197], off
	v_lshl_add_u64 v[196:197], s[24:25], 0, v[170:171]
	s_mov_b32 m0, s39
	s_nop 0
	global_load_lds_dwordx4 v[196:197], off
	s_waitcnt lgkmcnt(8)
	s_barrier
	s_waitcnt lgkmcnt(0)
	v_mfma_f32_16x16x32_bf16 v[124:127], v[128:131], v[144:147], v[124:127]
	v_mfma_f32_16x16x32_bf16 v[120:123], v[136:139], v[144:147], v[120:123]
	v_mfma_f32_16x16x32_bf16 v[108:111], v[128:131], v[152:155], v[108:111]
	v_mfma_f32_16x16x32_bf16 v[104:107], v[136:139], v[152:155], v[104:107]
	v_mfma_f32_16x16x32_bf16 v[92:95], v[128:131], v[160:163], v[92:95]
	v_mfma_f32_16x16x32_bf16 v[88:91], v[136:139], v[160:163], v[88:91]
	v_mfma_f32_16x16x32_bf16 v[76:79], v[128:131], v[184:187], v[76:79]
	v_mfma_f32_16x16x32_bf16 v[72:75], v[136:139], v[184:187], v[72:75]
	v_mfma_f32_16x16x32_bf16 v[124:127], v[132:135], v[148:151], v[124:127]
	v_mfma_f32_16x16x32_bf16 v[120:123], v[140:143], v[148:151], v[120:123]
	v_mfma_f32_16x16x32_bf16 v[108:111], v[132:135], v[156:159], v[108:111]
	v_mfma_f32_16x16x32_bf16 v[104:107], v[140:143], v[156:159], v[104:107]
	v_mfma_f32_16x16x32_bf16 v[92:95], v[132:135], v[164:167], v[92:95]
	v_mfma_f32_16x16x32_bf16 v[88:91], v[140:143], v[164:167], v[88:91]
	v_mfma_f32_16x16x32_bf16 v[76:79], v[132:135], v[188:191], v[76:79]
	v_mfma_f32_16x16x32_bf16 v[72:75], v[140:143], v[188:191], v[72:75]
	s_barrier
	s_add_i32 s24, 0, 0x1c000
	s_add_i32 s25, s26, s31
	v_add_u32_e32 v178, s24, v193
	v_lshl_add_u64 v[180:181], v[180:181], 0, s[40:41]
	s_mov_b32 m0, s25
	ds_read_b128 v[196:199], v178
	ds_read_b128 v[208:211], v178 offset:1024
	ds_read_b128 v[212:215], v178 offset:2048
	ds_read_b128 v[216:219], v178 offset:3072
	global_load_lds_dwordx4 v[180:181], off
	v_lshl_add_u64 v[180:181], v[200:201], 0, s[40:41]
	s_add_i32 m0, s25, 0x2000
	s_nop 0
	global_load_lds_dwordx4 v[180:181], off
	s_barrier
	s_waitcnt lgkmcnt(0)
	v_mfma_f32_16x16x32_bf16 v[116:119], v[196:199], v[144:147], v[116:119]
	v_mfma_f32_16x16x32_bf16 v[112:115], v[212:215], v[144:147], v[112:115]
	v_mfma_f32_16x16x32_bf16 v[100:103], v[196:199], v[152:155], v[100:103]
	v_mfma_f32_16x16x32_bf16 v[96:99], v[212:215], v[152:155], v[96:99]
	v_mfma_f32_16x16x32_bf16 v[84:87], v[196:199], v[160:163], v[84:87]
	v_mfma_f32_16x16x32_bf16 v[80:83], v[212:215], v[160:163], v[80:83]
	v_mfma_f32_16x16x32_bf16 v[68:71], v[196:199], v[184:187], v[68:71]
	v_mfma_f32_16x16x32_bf16 v[64:67], v[212:215], v[184:187], v[64:67]
	v_mfma_f32_16x16x32_bf16 v[116:119], v[208:211], v[148:151], v[116:119]
	v_mfma_f32_16x16x32_bf16 v[112:115], v[216:219], v[148:151], v[112:115]
	v_mfma_f32_16x16x32_bf16 v[100:103], v[208:211], v[156:159], v[100:103]
	v_mfma_f32_16x16x32_bf16 v[96:99], v[216:219], v[156:159], v[96:99]
	v_mfma_f32_16x16x32_bf16 v[84:87], v[208:211], v[164:167], v[84:87]
	v_mfma_f32_16x16x32_bf16 v[80:83], v[216:219], v[164:167], v[80:83]
	v_mfma_f32_16x16x32_bf16 v[68:71], v[208:211], v[188:191], v[68:71]
	v_mfma_f32_16x16x32_bf16 v[64:67], v[216:219], v[188:191], v[64:67]
	s_mov_b32 m0, s43
	v_lshl_add_u64 v[180:181], v[220:221], 0, s[40:41]
	s_barrier
	ds_read_b128 v[144:147], v195 offset:49152
	ds_read_b128 v[148:151], v195 offset:50176
	ds_read_b128 v[152:155], v195 offset:51200
	ds_read_b128 v[156:159], v195 offset:52224
	ds_read_b128 v[160:163], v195 offset:53248
	ds_read_b128 v[164:167], v195 offset:54272
	ds_read_b128 v[184:187], v195 offset:55296
	ds_read_b128 v[188:191], v195 offset:56320
	global_load_lds_dwordx4 v[180:181], off
	v_lshl_add_u64 v[180:181], v[222:223], 0, s[40:41]
	s_mov_b32 m0, s46
	s_nop 0
	global_load_lds_dwordx4 v[180:181], off
	s_barrier
	s_waitcnt lgkmcnt(0)
	v_mfma_f32_16x16x32_bf16 v[60:63], v[128:131], v[144:147], v[60:63]
	v_mfma_f32_16x16x32_bf16 v[56:59], v[136:139], v[144:147], v[56:59]
	v_mfma_f32_16x16x32_bf16 v[44:47], v[128:131], v[152:155], v[44:47]
	v_mfma_f32_16x16x32_bf16 v[40:43], v[136:139], v[152:155], v[40:43]
	v_mfma_f32_16x16x32_bf16 v[28:31], v[128:131], v[160:163], v[28:31]
	v_mfma_f32_16x16x32_bf16 v[24:27], v[136:139], v[160:163], v[24:27]
	v_mfma_f32_16x16x32_bf16 v[12:15], v[128:131], v[184:187], v[12:15]
	v_mfma_f32_16x16x32_bf16 v[8:11], v[136:139], v[184:187], v[8:11]
	v_mfma_f32_16x16x32_bf16 v[60:63], v[132:135], v[148:151], v[60:63]
	v_mfma_f32_16x16x32_bf16 v[56:59], v[140:143], v[148:151], v[56:59]
	v_mfma_f32_16x16x32_bf16 v[44:47], v[132:135], v[156:159], v[44:47]
	v_mfma_f32_16x16x32_bf16 v[40:43], v[140:143], v[156:159], v[40:43]
	v_mfma_f32_16x16x32_bf16 v[28:31], v[132:135], v[164:167], v[28:31]
	v_mfma_f32_16x16x32_bf16 v[24:27], v[140:143], v[164:167], v[24:27]
	v_mfma_f32_16x16x32_bf16 v[12:15], v[132:135], v[188:191], v[12:15]
	v_mfma_f32_16x16x32_bf16 v[8:11], v[140:143], v[188:191], v[8:11]
	s_barrier
	s_add_i32 s24, s24, s31
	v_lshl_add_u64 v[128:129], v[224:225], 0, s[40:41]
	s_mov_b32 m0, s24
	s_nop 0
	global_load_lds_dwordx4 v[128:129], off
	v_lshl_add_u64 v[128:129], v[226:227], 0, s[40:41]
	s_add_i32 m0, s24, 0x2000
	s_nop 0
	global_load_lds_dwordx4 v[128:129], off
	s_waitcnt vmcnt(6)
	s_barrier
	v_mfma_f32_16x16x32_bf16 v[52:55], v[196:199], v[144:147], v[52:55]
	v_mfma_f32_16x16x32_bf16 v[48:51], v[212:215], v[144:147], v[48:51]
	v_mfma_f32_16x16x32_bf16 v[36:39], v[196:199], v[152:155], v[36:39]
	v_mfma_f32_16x16x32_bf16 v[32:35], v[212:215], v[152:155], v[32:35]
	v_mfma_f32_16x16x32_bf16 v[20:23], v[196:199], v[160:163], v[20:23]
	v_mfma_f32_16x16x32_bf16 v[16:19], v[212:215], v[160:163], v[16:19]
	v_mfma_f32_16x16x32_bf16 v[4:7], v[196:199], v[184:187], v[4:7]
	v_mfma_f32_16x16x32_bf16 v[0:3], v[212:215], v[184:187], v[0:3]
	v_mfma_f32_16x16x32_bf16 v[52:55], v[208:211], v[148:151], v[52:55]
	v_mfma_f32_16x16x32_bf16 v[48:51], v[216:219], v[148:151], v[48:51]
	v_mfma_f32_16x16x32_bf16 v[36:39], v[208:211], v[156:159], v[36:39]
	v_mfma_f32_16x16x32_bf16 v[32:35], v[216:219], v[156:159], v[32:35]
	v_mfma_f32_16x16x32_bf16 v[20:23], v[208:211], v[164:167], v[20:23]
	v_mfma_f32_16x16x32_bf16 v[16:19], v[216:219], v[164:167], v[16:19]
	v_mfma_f32_16x16x32_bf16 v[4:7], v[208:211], v[188:191], v[4:7]
	v_mfma_f32_16x16x32_bf16 v[0:3], v[216:219], v[188:191], v[0:3]
	s_add_u32 s59, s59, 0x100
	s_addc_u32 s60, s60, 0
	s_add_u32 s8, s8, 0x100
	s_addc_u32 s9, s9, 0
	s_cmp_ge_u32 s61, s42
	s_mov_b32 s24, s61
	s_barrier
	s_cbranch_scc0 .LBB0_264
	s_sub_i32 s8, s57, 32
	s_lshr_b32 s8, s8, 3
	s_cmp_lt_i32 s57, 32
	s_cselect_b32 s26, 8, s8
	v_readlane_b32 s8, v255, 40
	v_readlane_b32 s9, v255, 41
	s_load_dwordx16 s[60:75], s[8:9], 0x0
	v_lshl_or_b32 v184, s58, 8, v194
	v_ashrrev_i32_e32 v185, 31, v184
	v_lshlrev_b64 v[128:129], 2, v[184:185]
	v_lshl_add_u32 v186, s57, 8, v192
	s_waitcnt lgkmcnt(0)
	s_cselect_b32 s24, s60, s50
	s_cselect_b32 s25, s61, s51
	s_add_i32 s8, s26, s53
	s_mul_hi_u32 s9, s8, 0xc000
	s_mul_i32 s8, s8, 0xc000
	s_add_u32 s8, s48, s8
	s_addc_u32 s9, s49, s9
	s_add_i32 s26, s54, s26
	s_mul_hi_u32 s27, s26, 0xc000
	s_mul_i32 s26, s26, 0xc000
	s_add_u32 s26, s48, s26
	s_addc_u32 s27, s49, s27
	v_lshl_add_u64 v[132:133], s[8:9], 0, v[128:129]
	v_lshl_add_u64 v[140:141], s[26:27], 0, v[128:129]
	global_load_dwordx4 v[144:147], v[132:133], off offset:16
	global_load_dwordx4 v[152:155], v[132:133], off
	global_load_dwordx4 v[148:151], v[140:141], off offset:16
	global_load_dwordx4 v[156:159], v[140:141], off
	global_load_dwordx4 v[128:131], v[132:133], off offset:528
	global_load_dwordx4 v[136:139], v[132:133], off offset:512
	s_nop 0
	global_load_dwordx4 v[132:135], v[140:141], off offset:528
	s_nop 0
	global_load_dwordx4 v[140:143], v[140:141], off offset:512
	v_lshl_add_u32 v196, v186, 11, v184
	v_lshlrev_b32_e32 v197, 2, v196
	v_lshlrev_b32_e32 v196, 1, v196
	s_and_b64 vcc, exec, s[4:5]
	s_cbranch_vccnz .Lres_f32
	global_load_dwordx4 v[164:167], v196, s[12:13]
	global_load_dwordx4 v[184:187], v196, s[12:13] offset:256
	s_add_u32 s62, s12, 0x10000
	s_addc_u32 s63, s13, 0
	global_load_dwordx4 v[188:191], v196, s[62:63]
	s_add_u32 s62, s12, 0x10000
	s_addc_u32 s63, s13, 0
	global_load_dwordx4 v[208:211], v196, s[62:63] offset:256
	s_add_u32 s62, s12, 0x20000
	s_addc_u32 s63, s13, 0
	global_load_dwordx4 v[212:215], v196, s[62:63]
	s_add_u32 s62, s12, 0x20000
	s_addc_u32 s63, s13, 0
	global_load_dwordx4 v[216:219], v196, s[62:63] offset:256
	s_add_u32 s62, s12, 0x30000
	s_addc_u32 s63, s13, 0
	global_load_dwordx4 v[220:223], v196, s[62:63]
	s_add_u32 s62, s12, 0x30000
	s_addc_u32 s63, s13, 0
	global_load_dwordx4 v[224:227], v196, s[62:63] offset:256
	s_waitcnt vmcnt(8)
	v_pk_add_f32 v[146:147], v[146:147], v[150:151]
	v_pk_add_f32 v[144:145], v[144:145], v[148:149]
	v_pk_add_f32 v[154:155], v[154:155], v[158:159]
	v_pk_add_f32 v[152:153], v[152:153], v[156:157]
	v_pk_add_f32 v[136:137], v[136:137], v[140:141]
	v_pk_add_f32 v[130:131], v[130:131], v[134:135]
	v_pk_add_f32 v[128:129], v[128:129], v[132:133]
	v_pk_add_f32 v[138:139], v[138:139], v[142:143]
	s_add_u32 s62, s12, 0x80000
	s_addc_u32 s63, s13, 0
	global_load_dwordx4 v[148:151], v196, s[62:63]
	s_add_u32 s62, s12, 0x80000
	s_addc_u32 s63, s13, 0
	global_load_dwordx4 v[156:159], v196, s[62:63] offset:256
	s_add_u32 s62, s12, 0x90000
	s_addc_u32 s63, s13, 0
	global_load_dwordx4 v[132:135], v196, s[62:63]
	s_add_u32 s62, s12, 0x90000
	s_addc_u32 s63, s13, 0
	global_load_dwordx4 v[140:143], v196, s[62:63] offset:256
	s_waitcnt vmcnt(11)
	v_lshlrev_b32_e32 v160, 16, v164
	v_and_b32_e32 v161, 0xffff0000, v164
	v_lshlrev_b32_e32 v162, 16, v165
	v_and_b32_e32 v163, 0xffff0000, v165
	v_lshlrev_b32_e32 v164, 16, v166
	v_and_b32_e32 v165, 0xffff0000, v166
	v_lshlrev_b32_e32 v166, 16, v167
	v_and_b32_e32 v167, 0xffff0000, v167
	v_pk_fma_f32 v[124:125], v[124:125], v[152:153], v[160:161]
	v_pk_fma_f32 v[126:127], v[126:127], v[154:155], v[162:163]
	v_pk_fma_f32 v[120:121], v[120:121], v[144:145], v[164:165]
	v_pk_fma_f32 v[122:123], v[122:123], v[146:147], v[166:167]
	s_add_u32 s62, s12, 0xa0000
	s_addc_u32 s63, s13, 0
	global_load_dwordx4 v[164:167], v196, s[62:63]
	v_cvt_pk_bf16_f32 v124, v124, v125
	v_cvt_pk_bf16_f32 v125, v126, v127
	v_cvt_pk_bf16_f32 v126, v120, v121
	v_cvt_pk_bf16_f32 v127, v122, v123
	global_store_dwordx4 v196, v[124:127], s[12:13]
	s_waitcnt vmcnt(12)
	v_lshlrev_b32_e32 v160, 16, v184
	v_and_b32_e32 v161, 0xffff0000, v184
	v_lshlrev_b32_e32 v162, 16, v185
	v_and_b32_e32 v163, 0xffff0000, v185
	v_lshlrev_b32_e32 v184, 16, v186
	v_and_b32_e32 v185, 0xffff0000, v186
	v_lshlrev_b32_e32 v186, 16, v187
	v_and_b32_e32 v187, 0xffff0000, v187
	v_pk_fma_f32 v[116:117], v[116:117], v[136:137], v[160:161]
	v_pk_fma_f32 v[118:119], v[118:119], v[138:139], v[162:163]
	v_pk_fma_f32 v[112:113], v[112:113], v[128:129], v[184:185]
	v_pk_fma_f32 v[114:115], v[114:115], v[130:131], v[186:187]
	s_add_u32 s62, s12, 0xa0000
	s_addc_u32 s63, s13, 0
	global_load_dwordx4 v[184:187], v196, s[62:63] offset:256
	v_cvt_pk_bf16_f32 v116, v116, v117
	v_cvt_pk_bf16_f32 v117, v118, v119
	v_cvt_pk_bf16_f32 v118, v112, v113
	v_cvt_pk_bf16_f32 v119, v114, v115
	global_store_dwordx4 v196, v[116:119], s[12:13] offset:256
	s_waitcnt vmcnt(13)
	v_lshlrev_b32_e32 v160, 16, v188
	v_and_b32_e32 v161, 0xffff0000, v188
	v_lshlrev_b32_e32 v162, 16, v189
	v_and_b32_e32 v163, 0xffff0000, v189
	v_lshlrev_b32_e32 v188, 16, v190
	v_and_b32_e32 v189, 0xffff0000, v190
	v_lshlrev_b32_e32 v190, 16, v191
	v_and_b32_e32 v191, 0xffff0000, v191
	v_pk_fma_f32 v[108:109], v[108:109], v[152:153], v[160:161]
	v_pk_fma_f32 v[110:111], v[110:111], v[154:155], v[162:163]
	v_pk_fma_f32 v[104:105], v[104:105], v[144:145], v[188:189]
	v_pk_fma_f32 v[106:107], v[106:107], v[146:147], v[190:191]
	s_add_u32 s62, s12, 0xb0000
	s_addc_u32 s63, s13, 0
	global_load_dwordx4 v[188:191], v196, s[62:63]
	v_cvt_pk_bf16_f32 v108, v108, v109
	v_cvt_pk_bf16_f32 v109, v110, v111
	v_cvt_pk_bf16_f32 v110, v104, v105
	v_cvt_pk_bf16_f32 v111, v106, v107
	s_add_u32 s64, s12, 0x10000
	s_addc_u32 s65, s13, 0
	global_store_dwordx4 v196, v[108:111], s[64:65]
	s_waitcnt vmcnt(14)
	v_lshlrev_b32_e32 v160, 16, v208
	v_and_b32_e32 v161, 0xffff0000, v208
	v_lshlrev_b32_e32 v162, 16, v209
	v_and_b32_e32 v163, 0xffff0000, v209
	v_lshlrev_b32_e32 v208, 16, v210
	v_and_b32_e32 v209, 0xffff0000, v210
	v_lshlrev_b32_e32 v210, 16, v211
	v_and_b32_e32 v211, 0xffff0000, v211
	v_pk_fma_f32 v[100:101], v[100:101], v[136:137], v[160:161]
	v_pk_fma_f32 v[102:103], v[102:103], v[138:139], v[162:163]
	v_pk_fma_f32 v[96:97], v[96:97], v[128:129], v[208:209]
	v_pk_fma_f32 v[98:99], v[98:99], v[130:131], v[210:211]
	s_add_u32 s62, s12, 0xb0000
	s_addc_u32 s63, s13, 0
	global_load_dwordx4 v[208:211], v196, s[62:63] offset:256
	v_cvt_pk_bf16_f32 v100, v100, v101
	v_cvt_pk_bf16_f32 v101, v102, v103
	v_cvt_pk_bf16_f32 v102, v96, v97
	v_cvt_pk_bf16_f32 v103, v98, v99
	s_add_u32 s64, s12, 0x10000
	s_addc_u32 s65, s13, 0
	global_store_dwordx4 v196, v[100:103], s[64:65] offset:256
	s_waitcnt vmcnt(15)
	v_lshlrev_b32_e32 v160, 16, v212
	v_and_b32_e32 v161, 0xffff0000, v212
	v_lshlrev_b32_e32 v162, 16, v213
	v_and_b32_e32 v163, 0xffff0000, v213
	v_lshlrev_b32_e32 v212, 16, v214
	v_and_b32_e32 v213, 0xffff0000, v214
	v_lshlrev_b32_e32 v214, 16, v215
	v_and_b32_e32 v215, 0xffff0000, v215
	v_pk_fma_f32 v[92:93], v[92:93], v[152:153], v[160:161]
	v_pk_fma_f32 v[94:95], v[94:95], v[154:155], v[162:163]
	v_pk_fma_f32 v[88:89], v[88:89], v[144:145], v[212:213]
	v_pk_fma_f32 v[90:91], v[90:91], v[146:147], v[214:215]
	v_cvt_pk_bf16_f32 v92, v92, v93
	v_cvt_pk_bf16_f32 v93, v94, v95
	v_cvt_pk_bf16_f32 v94, v88, v89
	v_cvt_pk_bf16_f32 v95, v90, v91
	s_add_u32 s64, s12, 0x20000
	s_addc_u32 s65, s13, 0
	global_store_dwordx4 v196, v[92:95], s[64:65]
	s_waitcnt vmcnt(15)
	v_lshlrev_b32_e32 v160, 16, v216
	v_and_b32_e32 v161, 0xffff0000, v216
	v_lshlrev_b32_e32 v162, 16, v217
	v_and_b32_e32 v163, 0xffff0000, v217
	v_lshlrev_b32_e32 v216, 16, v218
	v_and_b32_e32 v217, 0xffff0000, v218
	v_lshlrev_b32_e32 v218, 16, v219
	v_and_b32_e32 v219, 0xffff0000, v219
	v_pk_fma_f32 v[84:85], v[84:85], v[136:137], v[160:161]
	v_pk_fma_f32 v[86:87], v[86:87], v[138:139], v[162:163]
	v_pk_fma_f32 v[80:81], v[80:81], v[128:129], v[216:217]
	v_pk_fma_f32 v[82:83], v[82:83], v[130:131], v[218:219]
	v_cvt_pk_bf16_f32 v84, v84, v85
	v_cvt_pk_bf16_f32 v85, v86, v87
	v_cvt_pk_bf16_f32 v86, v80, v81
	v_cvt_pk_bf16_f32 v87, v82, v83
	s_add_u32 s64, s12, 0x20000
	s_addc_u32 s65, s13, 0
	global_store_dwordx4 v196, v[84:87], s[64:65] offset:256
	s_waitcnt vmcnt(15)
	v_lshlrev_b32_e32 v160, 16, v220
	v_and_b32_e32 v161, 0xffff0000, v220
	v_lshlrev_b32_e32 v162, 16, v221
	v_and_b32_e32 v163, 0xffff0000, v221
	v_lshlrev_b32_e32 v220, 16, v222
	v_and_b32_e32 v221, 0xffff0000, v222
	v_lshlrev_b32_e32 v222, 16, v223
	v_and_b32_e32 v223, 0xffff0000, v223
	v_pk_fma_f32 v[76:77], v[76:77], v[152:153], v[160:161]
	v_pk_fma_f32 v[78:79], v[78:79], v[154:155], v[162:163]
	v_pk_fma_f32 v[72:73], v[72:73], v[144:145], v[220:221]
	v_pk_fma_f32 v[74:75], v[74:75], v[146:147], v[222:223]
	v_cvt_pk_bf16_f32 v76, v76, v77
	v_cvt_pk_bf16_f32 v77, v78, v79
	v_cvt_pk_bf16_f32 v78, v72, v73
	v_cvt_pk_bf16_f32 v79, v74, v75
	s_add_u32 s64, s12, 0x30000
	s_addc_u32 s65, s13, 0
	global_store_dwordx4 v196, v[76:79], s[64:65]
	s_waitcnt vmcnt(15)
	v_lshlrev_b32_e32 v160, 16, v224
	v_and_b32_e32 v161, 0xffff0000, v224
	v_lshlrev_b32_e32 v162, 16, v225
	v_and_b32_e32 v163, 0xffff0000, v225
	v_lshlrev_b32_e32 v224, 16, v226
	v_and_b32_e32 v225, 0xffff0000, v226
	v_lshlrev_b32_e32 v226, 16, v227
	v_and_b32_e32 v227, 0xffff0000, v227
	v_pk_fma_f32 v[68:69], v[68:69], v[136:137], v[160:161]
	v_pk_fma_f32 v[70:71], v[70:71], v[138:139], v[162:163]
	v_pk_fma_f32 v[64:65], v[64:65], v[128:129], v[224:225]
	v_pk_fma_f32 v[66:67], v[66:67], v[130:131], v[226:227]
	v_cvt_pk_bf16_f32 v68, v68, v69
	v_cvt_pk_bf16_f32 v69, v70, v71
	v_cvt_pk_bf16_f32 v70, v64, v65
	v_cvt_pk_bf16_f32 v71, v66, v67
	s_add_u32 s64, s12, 0x30000
	s_addc_u32 s65, s13, 0
	global_store_dwordx4 v196, v[68:71], s[64:65] offset:256
	s_waitcnt vmcnt(15)
	v_lshlrev_b32_e32 v160, 16, v148
	v_and_b32_e32 v161, 0xffff0000, v148
	v_lshlrev_b32_e32 v162, 16, v149
	v_and_b32_e32 v163, 0xffff0000, v149
	v_lshlrev_b32_e32 v148, 16, v150
	v_and_b32_e32 v149, 0xffff0000, v150
	v_lshlrev_b32_e32 v150, 16, v151
	v_and_b32_e32 v151, 0xffff0000, v151
	v_pk_fma_f32 v[60:61], v[60:61], v[152:153], v[160:161]
	v_pk_fma_f32 v[62:63], v[62:63], v[154:155], v[162:163]
	v_pk_fma_f32 v[56:57], v[56:57], v[144:145], v[148:149]
	v_pk_fma_f32 v[58:59], v[58:59], v[146:147], v[150:151]
	v_cvt_pk_bf16_f32 v60, v60, v61
	v_cvt_pk_bf16_f32 v61, v62, v63
	v_cvt_pk_bf16_f32 v62, v56, v57
	v_cvt_pk_bf16_f32 v63, v58, v59
	s_add_u32 s64, s12, 0x80000
	s_addc_u32 s65, s13, 0
	global_store_dwordx4 v196, v[60:63], s[64:65]
	s_waitcnt vmcnt(15)
	v_lshlrev_b32_e32 v160, 16, v156
	v_and_b32_e32 v161, 0xffff0000, v156
	v_lshlrev_b32_e32 v162, 16, v157
	v_and_b32_e32 v163, 0xffff0000, v157
	v_lshlrev_b32_e32 v156, 16, v158
	v_and_b32_e32 v157, 0xffff0000, v158
	v_lshlrev_b32_e32 v158, 16, v159
	v_and_b32_e32 v159, 0xffff0000, v159
	v_pk_fma_f32 v[52:53], v[52:53], v[136:137], v[160:161]
	v_pk_fma_f32 v[54:55], v[54:55], v[138:139], v[162:163]
	v_pk_fma_f32 v[48:49], v[48:49], v[128:129], v[156:157]
	v_pk_fma_f32 v[50:51], v[50:51], v[130:131], v[158:159]
	v_cvt_pk_bf16_f32 v52, v52, v53
	v_cvt_pk_bf16_f32 v53, v54, v55
	v_cvt_pk_bf16_f32 v54, v48, v49
	v_cvt_pk_bf16_f32 v55, v50, v51
	s_add_u32 s64, s12, 0x80000
	s_addc_u32 s65, s13, 0
	global_store_dwordx4 v196, v[52:55], s[64:65] offset:256
	s_waitcnt vmcnt(15)
	v_lshlrev_b32_e32 v160, 16, v132
	v_and_b32_e32 v161, 0xffff0000, v132
	v_lshlrev_b32_e32 v162, 16, v133
	v_and_b32_e32 v163, 0xffff0000, v133
	v_lshlrev_b32_e32 v132, 16, v134
	v_and_b32_e32 v133, 0xffff0000, v134
	v_lshlrev_b32_e32 v134, 16, v135
	v_and_b32_e32 v135, 0xffff0000, v135
	v_pk_fma_f32 v[44:45], v[44:45], v[152:153], v[160:161]
	v_pk_fma_f32 v[46:47], v[46:47], v[154:155], v[162:163]
	v_pk_fma_f32 v[40:41], v[40:41], v[144:145], v[132:133]
	v_pk_fma_f32 v[42:43], v[42:43], v[146:147], v[134:135]
	v_cvt_pk_bf16_f32 v44, v44, v45
	v_cvt_pk_bf16_f32 v45, v46, v47
	v_cvt_pk_bf16_f32 v46, v40, v41
	v_cvt_pk_bf16_f32 v47, v42, v43
	s_add_u32 s64, s12, 0x90000
	s_addc_u32 s65, s13, 0
	global_store_dwordx4 v196, v[44:47], s[64:65]
	s_waitcnt vmcnt(15)
	v_lshlrev_b32_e32 v160, 16, v140
	v_and_b32_e32 v161, 0xffff0000, v140
	v_lshlrev_b32_e32 v162, 16, v141
	v_and_b32_e32 v163, 0xffff0000, v141
	v_lshlrev_b32_e32 v140, 16, v142
	v_and_b32_e32 v141, 0xffff0000, v142
	v_lshlrev_b32_e32 v142, 16, v143
	v_and_b32_e32 v143, 0xffff0000, v143
	v_pk_fma_f32 v[36:37], v[36:37], v[136:137], v[160:161]
	v_pk_fma_f32 v[38:39], v[38:39], v[138:139], v[162:163]
	v_pk_fma_f32 v[32:33], v[32:33], v[128:129], v[140:141]
	v_pk_fma_f32 v[34:35], v[34:35], v[130:131], v[142:143]
	v_cvt_pk_bf16_f32 v36, v36, v37
	v_cvt_pk_bf16_f32 v37, v38, v39
	v_cvt_pk_bf16_f32 v38, v32, v33
	v_cvt_pk_bf16_f32 v39, v34, v35
	s_add_u32 s64, s12, 0x90000
	s_addc_u32 s65, s13, 0
	global_store_dwordx4 v196, v[36:39], s[64:65] offset:256
	s_waitcnt vmcnt(15)
	v_lshlrev_b32_e32 v160, 16, v164
	v_and_b32_e32 v161, 0xffff0000, v164
	v_lshlrev_b32_e32 v162, 16, v165
	v_and_b32_e32 v163, 0xffff0000, v165
	v_lshlrev_b32_e32 v164, 16, v166
	v_and_b32_e32 v165, 0xffff0000, v166
	v_lshlrev_b32_e32 v166, 16, v167
	v_and_b32_e32 v167, 0xffff0000, v167
	v_pk_fma_f32 v[28:29], v[28:29], v[152:153], v[160:161]
	v_pk_fma_f32 v[30:31], v[30:31], v[154:155], v[162:163]
	v_pk_fma_f32 v[24:25], v[24:25], v[144:145], v[164:165]
	v_pk_fma_f32 v[26:27], v[26:27], v[146:147], v[166:167]
	v_cvt_pk_bf16_f32 v28, v28, v29
	v_cvt_pk_bf16_f32 v29, v30, v31
	v_cvt_pk_bf16_f32 v30, v24, v25
	v_cvt_pk_bf16_f32 v31, v26, v27
	s_add_u32 s64, s12, 0xa0000
	s_addc_u32 s65, s13, 0
	global_store_dwordx4 v196, v[28:31], s[64:65]
	s_waitcnt vmcnt(14)
	v_lshlrev_b32_e32 v160, 16, v184
	v_and_b32_e32 v161, 0xffff0000, v184
	v_lshlrev_b32_e32 v162, 16, v185
	v_and_b32_e32 v163, 0xffff0000, v185
	v_lshlrev_b32_e32 v184, 16, v186
	v_and_b32_e32 v185, 0xffff0000, v186
	v_lshlrev_b32_e32 v186, 16, v187
	v_and_b32_e32 v187, 0xffff0000, v187
	v_pk_fma_f32 v[20:21], v[20:21], v[136:137], v[160:161]
	v_pk_fma_f32 v[22:23], v[22:23], v[138:139], v[162:163]
	v_pk_fma_f32 v[16:17], v[16:17], v[128:129], v[184:185]
	v_pk_fma_f32 v[18:19], v[18:19], v[130:131], v[186:187]
	v_cvt_pk_bf16_f32 v20, v20, v21
	v_cvt_pk_bf16_f32 v21, v22, v23
	v_cvt_pk_bf16_f32 v22, v16, v17
	v_cvt_pk_bf16_f32 v23, v18, v19
	s_add_u32 s64, s12, 0xa0000
	s_addc_u32 s65, s13, 0
	global_store_dwordx4 v196, v[20:23], s[64:65] offset:256
	s_waitcnt vmcnt(13)
	v_lshlrev_b32_e32 v160, 16, v188
	v_and_b32_e32 v161, 0xffff0000, v188
	v_lshlrev_b32_e32 v162, 16, v189
	v_and_b32_e32 v163, 0xffff0000, v189
	v_lshlrev_b32_e32 v188, 16, v190
	v_and_b32_e32 v189, 0xffff0000, v190
	v_lshlrev_b32_e32 v190, 16, v191
	v_and_b32_e32 v191, 0xffff0000, v191
	v_pk_fma_f32 v[12:13], v[12:13], v[152:153], v[160:161]
	v_pk_fma_f32 v[14:15], v[14:15], v[154:155], v[162:163]
	v_pk_fma_f32 v[8:9], v[8:9], v[144:145], v[188:189]
	v_pk_fma_f32 v[10:11], v[10:11], v[146:147], v[190:191]
	v_cvt_pk_bf16_f32 v12, v12, v13
	v_cvt_pk_bf16_f32 v13, v14, v15
	v_cvt_pk_bf16_f32 v14, v8, v9
	v_cvt_pk_bf16_f32 v15, v10, v11
	s_add_u32 s64, s12, 0xb0000
	s_addc_u32 s65, s13, 0
	global_store_dwordx4 v196, v[12:15], s[64:65]
	s_waitcnt vmcnt(12)
	v_lshlrev_b32_e32 v160, 16, v208
	v_and_b32_e32 v161, 0xffff0000, v208
	v_lshlrev_b32_e32 v162, 16, v209
	v_and_b32_e32 v163, 0xffff0000, v209
	v_lshlrev_b32_e32 v208, 16, v210
	v_and_b32_e32 v209, 0xffff0000, v210
	v_lshlrev_b32_e32 v210, 16, v211
	v_and_b32_e32 v211, 0xffff0000, v211
	v_pk_fma_f32 v[4:5], v[4:5], v[136:137], v[160:161]
	v_pk_fma_f32 v[6:7], v[6:7], v[138:139], v[162:163]
	v_pk_fma_f32 v[0:1], v[0:1], v[128:129], v[208:209]
	v_pk_fma_f32 v[2:3], v[2:3], v[130:131], v[210:211]
	v_cvt_pk_bf16_f32 v4, v4, v5
	v_cvt_pk_bf16_f32 v5, v6, v7
	v_cvt_pk_bf16_f32 v6, v0, v1
	v_cvt_pk_bf16_f32 v7, v2, v3
	s_add_u32 s64, s12, 0xb0000
	s_addc_u32 s65, s13, 0
	global_store_dwordx4 v196, v[4:7], s[64:65] offset:256
	s_branch .Lres_done

.LBB0_639:
	s_add_i32 s60, s30, 2
	s_add_u32 s29, s26, 0x80
	s_addc_u32 s31, s27, 0
	s_add_i32 s34, 0, 0x10000
	v_add_u32_e32 v156, s34, v141
	ds_read_b128 v[144:147], v156
	ds_read_b128 v[148:151], v156 offset:1024
	ds_read_b128 v[152:155], v156 offset:2048
	ds_read_b128 v[156:159], v156 offset:3072
	s_cmp_eq_u32 s58, s30
	s_cselect_b32 s30, s20, s29
	s_cselect_b32 s31, s21, s31
	s_cselect_b32 s43, s25, s15
	s_cselect_b32 s42, s24, s13
	v_lshl_add_u64 v[196:197], s[26:27], 0, v[136:137]
	s_add_i32 m0, s17, 0xc000
	ds_read_b128 v[160:163], v143
	ds_read_b128 v[164:167], v143 offset:1024
	ds_read_b128 v[168:171], v143 offset:2048
	ds_read_b128 v[172:175], v143 offset:3072
	ds_read_b128 v[180:183], v143 offset:4096
	ds_read_b128 v[184:187], v143 offset:5120
	ds_read_b128 v[188:191], v143 offset:6144
	ds_read_b128 v[192:195], v143 offset:7168
	global_load_lds_dwordx4 v[196:197], off
	v_lshl_add_u64 v[196:197], s[26:27], 0, v[138:139]
	s_add_i32 m0, s17, 0xe000
	s_nop 0
	global_load_lds_dwordx4 v[196:197], off
	s_waitcnt lgkmcnt(8)
	s_barrier
	s_waitcnt lgkmcnt(0)
	v_mfma_f32_16x16x32_bf16 v[124:127], v[144:147], v[160:163], v[124:127]
	v_mfma_f32_16x16x32_bf16 v[120:123], v[152:155], v[160:163], v[120:123]
	v_mfma_f32_16x16x32_bf16 v[116:119], v[144:147], v[168:171], v[116:119]
	v_mfma_f32_16x16x32_bf16 v[112:115], v[152:155], v[168:171], v[112:115]
	v_mfma_f32_16x16x32_bf16 v[108:111], v[144:147], v[180:183], v[108:111]
	v_mfma_f32_16x16x32_bf16 v[104:107], v[152:155], v[180:183], v[104:107]
	v_mfma_f32_16x16x32_bf16 v[100:103], v[144:147], v[188:191], v[100:103]
	v_mfma_f32_16x16x32_bf16 v[96:99], v[152:155], v[188:191], v[96:99]
	v_mfma_f32_16x16x32_bf16 v[124:127], v[148:151], v[164:167], v[124:127]
	v_mfma_f32_16x16x32_bf16 v[120:123], v[156:159], v[164:167], v[120:123]
	v_mfma_f32_16x16x32_bf16 v[116:119], v[148:151], v[172:175], v[116:119]
	v_mfma_f32_16x16x32_bf16 v[112:115], v[156:159], v[172:175], v[112:115]
	v_mfma_f32_16x16x32_bf16 v[108:111], v[148:151], v[184:187], v[108:111]
	v_mfma_f32_16x16x32_bf16 v[104:107], v[156:159], v[184:187], v[104:107]
	v_mfma_f32_16x16x32_bf16 v[100:103], v[148:151], v[192:195], v[100:103]
	v_mfma_f32_16x16x32_bf16 v[96:99], v[156:159], v[192:195], v[96:99]
	s_barrier
	s_add_i32 s29, 0, 0x14000
	s_add_i32 s34, s34, s48
	v_add_u32_e32 v176, s29, v141
	v_lshl_add_u64 v[200:201], s[42:43], 0, v[130:131]
	s_mov_b32 m0, s34
	ds_read_b128 v[196:199], v176
	ds_read_b128 v[208:211], v176 offset:1024
	ds_read_b128 v[212:215], v176 offset:2048
	ds_read_b128 v[216:219], v176 offset:3072
	global_load_lds_dwordx4 v[200:201], off
	v_lshl_add_u64 v[220:221], s[42:43], 0, v[134:135]
	s_add_i32 m0, s34, 0x2000
	s_nop 0
	global_load_lds_dwordx4 v[220:221], off
	s_barrier
	s_waitcnt lgkmcnt(0)
	v_mfma_f32_16x16x32_bf16 v[72:75], v[196:199], v[160:163], v[72:75]
	v_mfma_f32_16x16x32_bf16 v[64:67], v[212:215], v[160:163], v[64:67]
	v_mfma_f32_16x16x32_bf16 v[56:59], v[196:199], v[168:171], v[56:59]
	v_mfma_f32_16x16x32_bf16 v[48:51], v[212:215], v[168:171], v[48:51]
	v_mfma_f32_16x16x32_bf16 v[44:47], v[196:199], v[180:183], v[44:47]
	v_mfma_f32_16x16x32_bf16 v[40:43], v[212:215], v[180:183], v[40:43]
	v_mfma_f32_16x16x32_bf16 v[36:39], v[196:199], v[188:191], v[36:39]
	v_mfma_f32_16x16x32_bf16 v[32:35], v[212:215], v[188:191], v[32:35]
	v_mfma_f32_16x16x32_bf16 v[72:75], v[208:211], v[164:167], v[72:75]
	v_mfma_f32_16x16x32_bf16 v[64:67], v[216:219], v[164:167], v[64:67]
	v_mfma_f32_16x16x32_bf16 v[56:59], v[208:211], v[172:175], v[56:59]
	v_mfma_f32_16x16x32_bf16 v[48:51], v[216:219], v[172:175], v[48:51]
	v_mfma_f32_16x16x32_bf16 v[44:47], v[208:211], v[184:187], v[44:47]
	v_mfma_f32_16x16x32_bf16 v[40:43], v[216:219], v[184:187], v[40:43]
	v_mfma_f32_16x16x32_bf16 v[36:39], v[208:211], v[192:195], v[36:39]
	v_mfma_f32_16x16x32_bf16 v[32:35], v[216:219], v[192:195], v[32:35]
	s_mov_b32 m0, s17
	v_lshl_add_u64 v[222:223], s[30:31], 0, v[128:129]
	s_barrier
	ds_read_b128 v[160:163], v143 offset:16384
	ds_read_b128 v[164:167], v143 offset:17408
	ds_read_b128 v[168:171], v143 offset:18432
	ds_read_b128 v[172:175], v143 offset:19456
	ds_read_b128 v[180:183], v143 offset:20480
	ds_read_b128 v[184:187], v143 offset:21504
	ds_read_b128 v[188:191], v143 offset:22528
	ds_read_b128 v[192:195], v143 offset:23552
	global_load_lds_dwordx4 v[222:223], off
	v_lshl_add_u64 v[224:225], s[30:31], 0, v[132:133]
	s_mov_b32 m0, s19
	s_nop 0
	global_load_lds_dwordx4 v[224:225], off
	s_barrier
	s_waitcnt lgkmcnt(0)
	v_mfma_f32_16x16x32_bf16 v[92:95], v[144:147], v[160:163], v[92:95]
	v_mfma_f32_16x16x32_bf16 v[88:91], v[152:155], v[160:163], v[88:91]
	v_mfma_f32_16x16x32_bf16 v[84:87], v[144:147], v[168:171], v[84:87]
	v_mfma_f32_16x16x32_bf16 v[80:83], v[152:155], v[168:171], v[80:83]
	v_mfma_f32_16x16x32_bf16 v[76:79], v[144:147], v[180:183], v[76:79]
	v_mfma_f32_16x16x32_bf16 v[68:71], v[152:155], v[180:183], v[68:71]
	v_mfma_f32_16x16x32_bf16 v[60:63], v[144:147], v[188:191], v[60:63]
	v_mfma_f32_16x16x32_bf16 v[52:55], v[152:155], v[188:191], v[52:55]
	v_mfma_f32_16x16x32_bf16 v[92:95], v[148:151], v[164:167], v[92:95]
	v_mfma_f32_16x16x32_bf16 v[88:91], v[156:159], v[164:167], v[88:91]
	v_mfma_f32_16x16x32_bf16 v[84:87], v[148:151], v[172:175], v[84:87]
	v_mfma_f32_16x16x32_bf16 v[80:83], v[156:159], v[172:175], v[80:83]
	v_mfma_f32_16x16x32_bf16 v[76:79], v[148:151], v[184:187], v[76:79]
	v_mfma_f32_16x16x32_bf16 v[68:71], v[156:159], v[184:187], v[68:71]
	v_mfma_f32_16x16x32_bf16 v[60:63], v[148:151], v[192:195], v[60:63]
	v_mfma_f32_16x16x32_bf16 v[52:55], v[156:159], v[192:195], v[52:55]
	s_barrier
	s_add_u32 s34, s42, s44
	s_addc_u32 s35, s43, 0
	s_add_i32 s29, s29, s48
	v_lshl_add_u64 v[226:227], s[34:35], 0, v[130:131]
	s_mov_b32 m0, s29
	v_lshl_add_u64 v[228:229], s[34:35], 0, v[134:135]
	global_load_lds_dwordx4 v[226:227], off
	s_add_i32 m0, s29, 0x2000
	s_nop 0
	global_load_lds_dwordx4 v[228:229], off
	s_waitcnt vmcnt(6)
	s_barrier
	v_mfma_f32_16x16x32_bf16 v[28:31], v[196:199], v[160:163], v[28:31]
	v_mfma_f32_16x16x32_bf16 v[24:27], v[212:215], v[160:163], v[24:27]
	v_mfma_f32_16x16x32_bf16 v[20:23], v[196:199], v[168:171], v[20:23]
	v_mfma_f32_16x16x32_bf16 v[16:19], v[212:215], v[168:171], v[16:19]
	v_mfma_f32_16x16x32_bf16 v[12:15], v[196:199], v[180:183], v[12:15]
	v_mfma_f32_16x16x32_bf16 v[8:11], v[212:215], v[180:183], v[8:11]
	v_mfma_f32_16x16x32_bf16 v[4:7], v[196:199], v[188:191], v[4:7]
	v_mfma_f32_16x16x32_bf16 v[0:3], v[212:215], v[188:191], v[0:3]
	v_mfma_f32_16x16x32_bf16 v[28:31], v[208:211], v[164:167], v[28:31]
	v_mfma_f32_16x16x32_bf16 v[24:27], v[216:219], v[164:167], v[24:27]
	v_mfma_f32_16x16x32_bf16 v[20:23], v[208:211], v[172:175], v[20:23]
	v_mfma_f32_16x16x32_bf16 v[16:19], v[216:219], v[172:175], v[16:19]
	v_mfma_f32_16x16x32_bf16 v[12:15], v[208:211], v[184:187], v[12:15]
	v_mfma_f32_16x16x32_bf16 v[8:11], v[216:219], v[184:187], v[8:11]
	v_mfma_f32_16x16x32_bf16 v[4:7], v[208:211], v[192:195], v[4:7]
	v_mfma_f32_16x16x32_bf16 v[0:3], v[216:219], v[192:195], v[0:3]
	s_add_i32 s29, 0, 0x18000
	v_add_u32_e32 v156, s29, v141
	s_barrier
	ds_read_b128 v[144:147], v156
	ds_read_b128 v[148:151], v156 offset:1024
	ds_read_b128 v[152:155], v156 offset:2048
	ds_read_b128 v[156:159], v156 offset:3072
	s_add_u32 s30, s30, s44
	s_addc_u32 s31, s31, 0
	s_mov_b32 m0, s51
	v_lshl_add_u64 v[196:197], s[30:31], 0, v[128:129]
	ds_read_b128 v[160:163], v143 offset:32768
	ds_read_b128 v[164:167], v143 offset:33792
	ds_read_b128 v[168:171], v143 offset:34816
	ds_read_b128 v[172:175], v143 offset:35840
	ds_read_b128 v[180:183], v143 offset:36864
	ds_read_b128 v[184:187], v143 offset:37888
	ds_read_b128 v[188:191], v143 offset:38912
	ds_read_b128 v[192:195], v143 offset:39936
	global_load_lds_dwordx4 v[196:197], off
	v_lshl_add_u64 v[196:197], s[30:31], 0, v[132:133]
	s_mov_b32 m0, s52
	s_nop 0
	global_load_lds_dwordx4 v[196:197], off
	s_waitcnt lgkmcnt(8)
	s_barrier
	s_waitcnt lgkmcnt(0)
	v_mfma_f32_16x16x32_bf16 v[124:127], v[144:147], v[160:163], v[124:127]
	v_mfma_f32_16x16x32_bf16 v[120:123], v[152:155], v[160:163], v[120:123]
	v_mfma_f32_16x16x32_bf16 v[116:119], v[144:147], v[168:171], v[116:119]
	v_mfma_f32_16x16x32_bf16 v[112:115], v[152:155], v[168:171], v[112:115]
	v_mfma_f32_16x16x32_bf16 v[108:111], v[144:147], v[180:183], v[108:111]
	v_mfma_f32_16x16x32_bf16 v[104:107], v[152:155], v[180:183], v[104:107]
	v_mfma_f32_16x16x32_bf16 v[100:103], v[144:147], v[188:191], v[100:103]
	v_mfma_f32_16x16x32_bf16 v[96:99], v[152:155], v[188:191], v[96:99]
	v_mfma_f32_16x16x32_bf16 v[124:127], v[148:151], v[164:167], v[124:127]
	v_mfma_f32_16x16x32_bf16 v[120:123], v[156:159], v[164:167], v[120:123]
	v_mfma_f32_16x16x32_bf16 v[116:119], v[148:151], v[172:175], v[116:119]
	v_mfma_f32_16x16x32_bf16 v[112:115], v[156:159], v[172:175], v[112:115]
	v_mfma_f32_16x16x32_bf16 v[108:111], v[148:151], v[184:187], v[108:111]
	v_mfma_f32_16x16x32_bf16 v[104:107], v[156:159], v[184:187], v[104:107]
	v_mfma_f32_16x16x32_bf16 v[100:103], v[148:151], v[192:195], v[100:103]
	v_mfma_f32_16x16x32_bf16 v[96:99], v[156:159], v[192:195], v[96:99]
	s_barrier
	s_add_i32 s30, 0, 0x1c000
	s_add_i32 s29, s29, s48
	v_add_u32_e32 v176, s30, v141
	v_lshl_add_u64 v[200:201], v[200:201], 0, s[40:41]
	s_mov_b32 m0, s29
	ds_read_b128 v[196:199], v176
	ds_read_b128 v[208:211], v176 offset:1024
	ds_read_b128 v[212:215], v176 offset:2048
	ds_read_b128 v[216:219], v176 offset:3072
	global_load_lds_dwordx4 v[200:201], off
	v_lshl_add_u64 v[200:201], v[220:221], 0, s[40:41]
	s_add_i32 m0, s29, 0x2000
	s_nop 0
	global_load_lds_dwordx4 v[200:201], off
	s_barrier
	s_waitcnt lgkmcnt(0)
	v_mfma_f32_16x16x32_bf16 v[72:75], v[196:199], v[160:163], v[72:75]
	v_mfma_f32_16x16x32_bf16 v[64:67], v[212:215], v[160:163], v[64:67]
	v_mfma_f32_16x16x32_bf16 v[56:59], v[196:199], v[168:171], v[56:59]
	v_mfma_f32_16x16x32_bf16 v[48:51], v[212:215], v[168:171], v[48:51]
	v_mfma_f32_16x16x32_bf16 v[44:47], v[196:199], v[180:183], v[44:47]
	v_mfma_f32_16x16x32_bf16 v[40:43], v[212:215], v[180:183], v[40:43]
	v_mfma_f32_16x16x32_bf16 v[36:39], v[196:199], v[188:191], v[36:39]
	v_mfma_f32_16x16x32_bf16 v[32:35], v[212:215], v[188:191], v[32:35]
	v_mfma_f32_16x16x32_bf16 v[72:75], v[208:211], v[164:167], v[72:75]
	v_mfma_f32_16x16x32_bf16 v[64:67], v[216:219], v[164:167], v[64:67]
	v_mfma_f32_16x16x32_bf16 v[56:59], v[208:211], v[172:175], v[56:59]
	v_mfma_f32_16x16x32_bf16 v[48:51], v[216:219], v[172:175], v[48:51]
	v_mfma_f32_16x16x32_bf16 v[44:47], v[208:211], v[184:187], v[44:47]
	v_mfma_f32_16x16x32_bf16 v[40:43], v[216:219], v[184:187], v[40:43]
	v_mfma_f32_16x16x32_bf16 v[36:39], v[208:211], v[192:195], v[36:39]
	v_mfma_f32_16x16x32_bf16 v[32:35], v[216:219], v[192:195], v[32:35]
	s_mov_b32 m0, s56
	v_lshl_add_u64 v[200:201], v[222:223], 0, s[40:41]
	s_barrier
	ds_read_b128 v[160:163], v143 offset:49152
	ds_read_b128 v[164:167], v143 offset:50176
	ds_read_b128 v[168:171], v143 offset:51200
	ds_read_b128 v[172:175], v143 offset:52224
	ds_read_b128 v[180:183], v143 offset:53248
	ds_read_b128 v[184:187], v143 offset:54272
	ds_read_b128 v[188:191], v143 offset:55296
	ds_read_b128 v[192:195], v143 offset:56320
	global_load_lds_dwordx4 v[200:201], off
	v_lshl_add_u64 v[200:201], v[224:225], 0, s[40:41]
	s_mov_b32 m0, s57
	s_nop 0
	global_load_lds_dwordx4 v[200:201], off
	s_barrier
	s_waitcnt lgkmcnt(0)
	v_mfma_f32_16x16x32_bf16 v[92:95], v[144:147], v[160:163], v[92:95]
	v_mfma_f32_16x16x32_bf16 v[88:91], v[152:155], v[160:163], v[88:91]
	v_mfma_f32_16x16x32_bf16 v[84:87], v[144:147], v[168:171], v[84:87]
	v_mfma_f32_16x16x32_bf16 v[80:83], v[152:155], v[168:171], v[80:83]
	v_mfma_f32_16x16x32_bf16 v[76:79], v[144:147], v[180:183], v[76:79]
	v_mfma_f32_16x16x32_bf16 v[68:71], v[152:155], v[180:183], v[68:71]
	v_mfma_f32_16x16x32_bf16 v[60:63], v[144:147], v[188:191], v[60:63]
	v_mfma_f32_16x16x32_bf16 v[52:55], v[152:155], v[188:191], v[52:55]
	v_mfma_f32_16x16x32_bf16 v[92:95], v[148:151], v[164:167], v[92:95]
	v_mfma_f32_16x16x32_bf16 v[88:91], v[156:159], v[164:167], v[88:91]
	v_mfma_f32_16x16x32_bf16 v[84:87], v[148:151], v[172:175], v[84:87]
	v_mfma_f32_16x16x32_bf16 v[80:83], v[156:159], v[172:175], v[80:83]
	v_mfma_f32_16x16x32_bf16 v[76:79], v[148:151], v[184:187], v[76:79]
	v_mfma_f32_16x16x32_bf16 v[68:71], v[156:159], v[184:187], v[68:71]
	v_mfma_f32_16x16x32_bf16 v[60:63], v[148:151], v[192:195], v[60:63]
	v_mfma_f32_16x16x32_bf16 v[52:55], v[156:159], v[192:195], v[52:55]
	s_barrier
	s_add_i32 s29, s30, s48
	v_lshl_add_u64 v[144:145], v[226:227], 0, s[40:41]
	s_mov_b32 m0, s29
	s_nop 0
	global_load_lds_dwordx4 v[144:145], off
	v_lshl_add_u64 v[144:145], v[228:229], 0, s[40:41]
	s_add_i32 m0, s29, 0x2000
	s_nop 0
	global_load_lds_dwordx4 v[144:145], off
	s_waitcnt vmcnt(6)
	s_barrier
	v_mfma_f32_16x16x32_bf16 v[28:31], v[196:199], v[160:163], v[28:31]
	v_mfma_f32_16x16x32_bf16 v[24:27], v[212:215], v[160:163], v[24:27]
	v_mfma_f32_16x16x32_bf16 v[20:23], v[196:199], v[168:171], v[20:23]
	v_mfma_f32_16x16x32_bf16 v[16:19], v[212:215], v[168:171], v[16:19]
	v_mfma_f32_16x16x32_bf16 v[12:15], v[196:199], v[180:183], v[12:15]
	v_mfma_f32_16x16x32_bf16 v[8:11], v[212:215], v[180:183], v[8:11]
	v_mfma_f32_16x16x32_bf16 v[4:7], v[196:199], v[188:191], v[4:7]
	v_mfma_f32_16x16x32_bf16 v[0:3], v[212:215], v[188:191], v[0:3]
	v_mfma_f32_16x16x32_bf16 v[28:31], v[208:211], v[164:167], v[28:31]
	v_mfma_f32_16x16x32_bf16 v[24:27], v[216:219], v[164:167], v[24:27]
	v_mfma_f32_16x16x32_bf16 v[20:23], v[208:211], v[172:175], v[20:23]
	v_mfma_f32_16x16x32_bf16 v[16:19], v[216:219], v[172:175], v[16:19]
	v_mfma_f32_16x16x32_bf16 v[12:15], v[208:211], v[184:187], v[12:15]
	v_mfma_f32_16x16x32_bf16 v[8:11], v[216:219], v[184:187], v[8:11]
	v_mfma_f32_16x16x32_bf16 v[4:7], v[208:211], v[192:195], v[4:7]
	v_mfma_f32_16x16x32_bf16 v[0:3], v[216:219], v[192:195], v[0:3]
	s_add_u32 s26, s26, 0x100
	s_addc_u32 s27, s27, 0
	s_add_u32 s13, s13, 0x100
	s_addc_u32 s15, s15, 0
	s_cmp_ge_u32 s60, s55
	s_mov_b32 s30, s60
	s_barrier
	s_cbranch_scc0 .LBB0_639
	s_lshl_b32 s13, s16, 8
	s_ashr_i32 s15, s16, 1
	s_and_b32 s13, s13, 0x100
	v_or_b32_e32 v145, s13, v142
	s_lshl_b32 s13, s15, s59
	s_add_i32 s26, s13, s54
	s_ashr_i32 s27, s26, 31
	s_lshl_b64 s[26:27], s[26:27], 12
	v_readlane_b32 s30, v255, 26
	v_lshl_add_u32 v144, s18, 8, v140
	v_readlane_b32 s31, v255, 27
	s_add_u32 s26, s30, s26
	s_addc_u32 s27, s31, s27
	v_lshlrev_b32_e32 v176, 1, v145
	v_pk_mul_f32 v[124:125], s[8:9], v[124:125]
	v_ashrrev_i32_e32 v145, 31, v144
	v_lshl_add_u64 v[146:147], s[26:27], 0, v[176:177]
	v_pk_mul_f32 v[148:149], s[10:11], v[122:123]
	v_pk_mul_f32 v[122:123], s[8:9], v[120:121]
	v_cvt_pk_bf16_f32 v120, v124, v125
	v_lshlrev_b64 v[124:125], 12, v[144:145]
	v_pk_mul_f32 v[126:127], s[10:11], v[126:127]
	v_lshl_add_u64 v[124:125], v[146:147], 0, v[124:125]
	v_cvt_pk_bf16_f32 v121, v126, v127
	v_pk_mul_f32 v[116:117], s[8:9], v[116:117]
	v_cvt_pk_bf16_f32 v122, v122, v123
	v_cvt_pk_bf16_f32 v123, v148, v149
	global_store_dwordx4 v[124:125], v[120:123], off offset:3072
	v_pk_mul_f32 v[118:119], s[10:11], v[118:119]
	v_pk_mul_f32 v[108:109], s[8:9], v[108:109]
	v_pk_mul_f32 v[120:121], s[10:11], v[114:115]
	v_pk_mul_f32 v[114:115], s[8:9], v[112:113]
	v_cvt_pk_bf16_f32 v112, v116, v117
	v_or_b32_e32 v116, 16, v144
	v_ashrrev_i32_e32 v117, 31, v116
	v_lshlrev_b64 v[116:117], 12, v[116:117]
	v_cvt_pk_bf16_f32 v113, v118, v119
	v_lshl_add_u64 v[116:117], v[146:147], 0, v[116:117]
	v_cvt_pk_bf16_f32 v114, v114, v115
	v_cvt_pk_bf16_f32 v115, v120, v121
	global_store_dwordx4 v[116:117], v[112:115], off offset:3072
	v_pk_mul_f32 v[110:111], s[10:11], v[110:111]
	v_pk_mul_f32 v[100:101], s[8:9], v[100:101]
	v_pk_mul_f32 v[112:113], s[10:11], v[106:107]
	v_pk_mul_f32 v[106:107], s[8:9], v[104:105]
	v_cvt_pk_bf16_f32 v104, v108, v109
	v_or_b32_e32 v108, 32, v144
	v_ashrrev_i32_e32 v109, 31, v108
	v_lshlrev_b64 v[108:109], 12, v[108:109]
	v_cvt_pk_bf16_f32 v105, v110, v111
	v_lshl_add_u64 v[108:109], v[146:147], 0, v[108:109]
	v_cvt_pk_bf16_f32 v106, v106, v107
	v_cvt_pk_bf16_f32 v107, v112, v113
	global_store_dwordx4 v[108:109], v[104:107], off offset:3072
	v_pk_mul_f32 v[102:103], s[10:11], v[102:103]
	v_pk_mul_f32 v[92:93], s[8:9], v[92:93]
	v_pk_mul_f32 v[104:105], s[10:11], v[98:99]
	v_pk_mul_f32 v[98:99], s[8:9], v[96:97]
	v_cvt_pk_bf16_f32 v96, v100, v101
	v_or_b32_e32 v100, 48, v144
	v_ashrrev_i32_e32 v101, 31, v100
	v_lshlrev_b64 v[100:101], 12, v[100:101]
	v_cvt_pk_bf16_f32 v97, v102, v103
	v_lshl_add_u64 v[100:101], v[146:147], 0, v[100:101]
	s_mov_b64 s[26:27], 0x80000
	v_cvt_pk_bf16_f32 v98, v98, v99
	v_cvt_pk_bf16_f32 v99, v104, v105
	global_store_dwordx4 v[100:101], v[96:99], off offset:3072
	v_pk_mul_f32 v[94:95], s[10:11], v[94:95]
	v_pk_mul_f32 v[84:85], s[8:9], v[84:85]
	v_pk_mul_f32 v[96:97], s[10:11], v[90:91]
	v_pk_mul_f32 v[90:91], s[8:9], v[88:89]
	v_cvt_pk_bf16_f32 v88, v92, v93
	v_cvt_pk_bf16_f32 v89, v94, v95
	v_lshl_add_u64 v[92:93], v[124:125], 0, s[26:27]
	s_mov_b64 s[26:27], 0x90000
	v_cvt_pk_bf16_f32 v90, v90, v91
	v_cvt_pk_bf16_f32 v91, v96, v97
	global_store_dwordx4 v[92:93], v[88:91], off offset:3072
	v_pk_mul_f32 v[86:87], s[10:11], v[86:87]
	v_pk_mul_f32 v[76:77], s[8:9], v[76:77]
	v_pk_mul_f32 v[88:89], s[10:11], v[82:83]
	v_pk_mul_f32 v[82:83], s[8:9], v[80:81]
	v_cvt_pk_bf16_f32 v80, v84, v85
	v_cvt_pk_bf16_f32 v81, v86, v87
	v_lshl_add_u64 v[84:85], v[124:125], 0, s[26:27]
	s_mov_b64 s[26:27], 0xa0000
	v_cvt_pk_bf16_f32 v82, v82, v83
	v_cvt_pk_bf16_f32 v83, v88, v89
	global_store_dwordx4 v[84:85], v[80:83], off offset:3072
	v_pk_mul_f32 v[78:79], s[10:11], v[78:79]
	v_pk_mul_f32 v[60:61], s[8:9], v[60:61]
	v_pk_mul_f32 v[80:81], s[10:11], v[70:71]
	v_pk_mul_f32 v[70:71], s[8:9], v[68:69]
	v_cvt_pk_bf16_f32 v68, v76, v77
	v_cvt_pk_bf16_f32 v69, v78, v79
	v_lshl_add_u64 v[76:77], v[124:125], 0, s[26:27]
	v_cvt_pk_bf16_f32 v70, v70, v71
	v_cvt_pk_bf16_f32 v71, v80, v81
	global_store_dwordx4 v[76:77], v[68:71], off offset:3072
	s_mov_b64 s[26:27], 0xb0000
	v_pk_mul_f32 v[62:63], s[10:11], v[62:63]
	v_pk_mul_f32 v[68:69], s[10:11], v[54:55]
	v_pk_mul_f32 v[54:55], s[8:9], v[52:53]
	v_cvt_pk_bf16_f32 v52, v60, v61
	v_cvt_pk_bf16_f32 v53, v62, v63
	v_lshl_add_u64 v[60:61], v[124:125], 0, s[26:27]
	v_cvt_pk_bf16_f32 v54, v54, v55
	v_cvt_pk_bf16_f32 v55, v68, v69
	global_store_dwordx4 v[60:61], v[52:55], off offset:3072
	v_pk_mul_f32 v[62:63], s[10:11], v[66:67]
	v_pk_mul_f32 v[64:65], s[8:9], v[64:65]
	v_pk_mul_f32 v[54:55], s[10:11], v[74:75]
	v_pk_mul_f32 v[52:53], s[8:9], v[72:73]
	v_pk_mul_f32 v[46:47], s[10:11], v[46:47]
	v_cvt_pk_bf16_f32 v52, v52, v53
	v_cvt_pk_bf16_f32 v53, v54, v55
	v_cvt_pk_bf16_f32 v54, v64, v65
	v_cvt_pk_bf16_f32 v55, v62, v63
	global_store_dwordx4 v[124:125], v[52:55], off offset:3328
	v_pk_mul_f32 v[44:45], s[8:9], v[44:45]
	v_pk_mul_f32 v[38:39], s[10:11], v[38:39]
	v_pk_mul_f32 v[52:53], s[10:11], v[58:59]
	v_pk_mul_f32 v[54:55], s[8:9], v[56:57]
	v_pk_mul_f32 v[56:57], s[10:11], v[50:51]
	v_pk_mul_f32 v[50:51], s[8:9], v[48:49]
	v_cvt_pk_bf16_f32 v48, v54, v55
	v_cvt_pk_bf16_f32 v49, v52, v53
	v_pk_mul_f32 v[36:37], s[8:9], v[36:37]
	v_cvt_pk_bf16_f32 v50, v50, v51
	v_cvt_pk_bf16_f32 v51, v56, v57
	global_store_dwordx4 v[116:117], v[48:51], off offset:3328
	v_pk_mul_f32 v[30:31], s[10:11], v[30:31]
	v_pk_mul_f32 v[28:29], s[8:9], v[28:29]
	v_pk_mul_f32 v[48:49], s[10:11], v[42:43]
	v_pk_mul_f32 v[42:43], s[8:9], v[40:41]
	v_cvt_pk_bf16_f32 v40, v44, v45
	v_cvt_pk_bf16_f32 v41, v46, v47
	v_pk_mul_f32 v[22:23], s[10:11], v[22:23]
	v_cvt_pk_bf16_f32 v42, v42, v43
	v_cvt_pk_bf16_f32 v43, v48, v49
	global_store_dwordx4 v[108:109], v[40:43], off offset:3328
	v_pk_mul_f32 v[20:21], s[8:9], v[20:21]
	v_pk_mul_f32 v[14:15], s[10:11], v[14:15]
	v_pk_mul_f32 v[40:41], s[10:11], v[34:35]
	v_pk_mul_f32 v[34:35], s[8:9], v[32:33]
	v_cvt_pk_bf16_f32 v32, v36, v37
	v_cvt_pk_bf16_f32 v33, v38, v39
	v_pk_mul_f32 v[12:13], s[8:9], v[12:13]
	v_cvt_pk_bf16_f32 v34, v34, v35
	v_cvt_pk_bf16_f32 v35, v40, v41
	global_store_dwordx4 v[100:101], v[32:35], off offset:3328
	s_and_b64 vcc, exec, s[6:7]
	s_mov_b32 s16, s12
	v_pk_mul_f32 v[32:33], s[10:11], v[26:27]
	v_pk_mul_f32 v[26:27], s[8:9], v[24:25]
	v_cvt_pk_bf16_f32 v24, v28, v29
	v_cvt_pk_bf16_f32 v25, v30, v31
	s_mov_b32 s18, s14
	v_cvt_pk_bf16_f32 v26, v26, v27
	v_cvt_pk_bf16_f32 v27, v32, v33
	global_store_dwordx4 v[92:93], v[24:27], off offset:3328
	s_mov_b64 s[30:31], s[24:25]
	s_mov_b64 s[26:27], s[20:21]
	v_pk_mul_f32 v[24:25], s[10:11], v[18:19]
	v_pk_mul_f32 v[18:19], s[8:9], v[16:17]
	v_cvt_pk_bf16_f32 v16, v20, v21
	v_cvt_pk_bf16_f32 v17, v22, v23
	v_pk_mul_f32 v[6:7], s[10:11], v[6:7]
	v_cvt_pk_bf16_f32 v18, v18, v19
	v_cvt_pk_bf16_f32 v19, v24, v25
	global_store_dwordx4 v[84:85], v[16:19], off offset:3328
	v_pk_mul_f32 v[4:5], s[8:9], v[4:5]
	s_nop 0
	v_pk_mul_f32 v[16:17], s[10:11], v[10:11]
	v_pk_mul_f32 v[10:11], s[8:9], v[8:9]
	v_cvt_pk_bf16_f32 v8, v12, v13
	v_cvt_pk_bf16_f32 v9, v14, v15
	s_nop 0
	v_cvt_pk_bf16_f32 v10, v10, v11
	v_cvt_pk_bf16_f32 v11, v16, v17
	global_store_dwordx4 v[76:77], v[8:11], off offset:3328
	s_nop 1
	v_pk_mul_f32 v[8:9], s[10:11], v[2:3]
	v_pk_mul_f32 v[2:3], s[8:9], v[0:1]
	v_cvt_pk_bf16_f32 v0, v4, v5
	v_cvt_pk_bf16_f32 v1, v6, v7
	s_nop 0
	v_cvt_pk_bf16_f32 v2, v2, v3
	v_cvt_pk_bf16_f32 v3, v8, v9
	global_store_dwordx4 v[60:61], v[0:3], off offset:3328
	s_cbranch_vccz .LBB0_636
	s_waitcnt vmcnt(0)
	s_setprio 0
	s_cmpk_gt_u32 s1, 0xff
	s_cbranch_scc1 .LBB0_626
	s_barrier
	s_branch .LBB0_626

.LBB0_656:
	s_add_u32 s20, s18, 0xfff80080
	s_addc_u32 s21, s19, -1
	s_add_i32 s34, 0, 0x10000
	v_add_u32_e32 v152, s34, v174
	ds_read_b128 v[140:143], v152
	ds_read_b128 v[144:147], v152 offset:1024
	ds_read_b128 v[148:151], v152 offset:2048
	ds_read_b128 v[152:155], v152 offset:3072
	s_cmp_eq_u32 s54, 28
	s_cselect_b32 s25, s9, s21
	s_cselect_b32 s24, s15, s20
	s_cselect_b32 s21, s5, s53
	s_cselect_b32 s20, s17, s44
	v_lshl_add_u64 v[180:181], s[18:19], 0, v[136:137]
	s_add_i32 m0, s30, 0xc000
	ds_read_b128 v[156:159], v189
	ds_read_b128 v[160:163], v189 offset:1024
	ds_read_b128 v[164:167], v189 offset:2048
	ds_read_b128 v[168:171], v189 offset:3072
	ds_read_b128 v[190:193], v189 offset:4096
	ds_read_b128 v[194:197], v189 offset:5120
	ds_read_b128 v[198:201], v189 offset:6144
	ds_read_b128 v[208:211], v189 offset:7168
	global_load_lds_dwordx4 v[180:181], off
	v_lshl_add_u64 v[180:181], s[18:19], 0, v[138:139]
	s_add_i32 m0, s30, 0xe000
	s_nop 0
	global_load_lds_dwordx4 v[180:181], off
	s_waitcnt lgkmcnt(8)
	s_barrier
	s_waitcnt lgkmcnt(0)
	v_mfma_f32_16x16x32_bf16 v[124:127], v[140:143], v[156:159], v[124:127]
	v_mfma_f32_16x16x32_bf16 v[120:123], v[148:151], v[156:159], v[120:123]
	v_mfma_f32_16x16x32_bf16 v[108:111], v[140:143], v[164:167], v[108:111]
	v_mfma_f32_16x16x32_bf16 v[104:107], v[148:151], v[164:167], v[104:107]
	v_mfma_f32_16x16x32_bf16 v[92:95], v[140:143], v[190:193], v[92:95]
	v_mfma_f32_16x16x32_bf16 v[88:91], v[148:151], v[190:193], v[88:91]
	v_mfma_f32_16x16x32_bf16 v[76:79], v[140:143], v[198:201], v[76:79]
	v_mfma_f32_16x16x32_bf16 v[72:75], v[148:151], v[198:201], v[72:75]
	v_mfma_f32_16x16x32_bf16 v[124:127], v[144:147], v[160:163], v[124:127]
	v_mfma_f32_16x16x32_bf16 v[120:123], v[152:155], v[160:163], v[120:123]
	v_mfma_f32_16x16x32_bf16 v[108:111], v[144:147], v[168:171], v[108:111]
	v_mfma_f32_16x16x32_bf16 v[104:107], v[152:155], v[168:171], v[104:107]
	v_mfma_f32_16x16x32_bf16 v[92:95], v[144:147], v[194:197], v[92:95]
	v_mfma_f32_16x16x32_bf16 v[88:91], v[152:155], v[194:197], v[88:91]
	v_mfma_f32_16x16x32_bf16 v[76:79], v[144:147], v[208:211], v[76:79]
	v_mfma_f32_16x16x32_bf16 v[72:75], v[152:155], v[208:211], v[72:75]
	s_barrier
	s_add_i32 s35, 0, 0x14000
	s_add_i32 s34, s34, s28
	v_add_u32_e32 v176, s35, v174
	v_lshl_add_u64 v[180:181], s[20:21], 0, v[130:131]
	s_mov_b32 m0, s34
	ds_read_b128 v[212:215], v176
	ds_read_b128 v[216:219], v176 offset:1024
	ds_read_b128 v[220:223], v176 offset:2048
	ds_read_b128 v[224:227], v176 offset:3072
	global_load_lds_dwordx4 v[180:181], off
	v_lshl_add_u64 v[228:229], s[20:21], 0, v[134:135]
	s_add_i32 m0, s34, 0x2000
	s_nop 0
	global_load_lds_dwordx4 v[228:229], off
	s_barrier
	s_waitcnt lgkmcnt(0)
	v_mfma_f32_16x16x32_bf16 v[116:119], v[212:215], v[156:159], v[116:119]
	v_mfma_f32_16x16x32_bf16 v[112:115], v[220:223], v[156:159], v[112:115]
	v_mfma_f32_16x16x32_bf16 v[100:103], v[212:215], v[164:167], v[100:103]
	v_mfma_f32_16x16x32_bf16 v[96:99], v[220:223], v[164:167], v[96:99]
	v_mfma_f32_16x16x32_bf16 v[84:87], v[212:215], v[190:193], v[84:87]
	v_mfma_f32_16x16x32_bf16 v[80:83], v[220:223], v[190:193], v[80:83]
	v_mfma_f32_16x16x32_bf16 v[68:71], v[212:215], v[198:201], v[68:71]
	v_mfma_f32_16x16x32_bf16 v[64:67], v[220:223], v[198:201], v[64:67]
	v_mfma_f32_16x16x32_bf16 v[116:119], v[216:219], v[160:163], v[116:119]
	v_mfma_f32_16x16x32_bf16 v[112:115], v[224:227], v[160:163], v[112:115]
	v_mfma_f32_16x16x32_bf16 v[100:103], v[216:219], v[168:171], v[100:103]
	v_mfma_f32_16x16x32_bf16 v[96:99], v[224:227], v[168:171], v[96:99]
	v_mfma_f32_16x16x32_bf16 v[84:87], v[216:219], v[194:197], v[84:87]
	v_mfma_f32_16x16x32_bf16 v[80:83], v[224:227], v[194:197], v[80:83]
	v_mfma_f32_16x16x32_bf16 v[68:71], v[216:219], v[208:211], v[68:71]
	v_mfma_f32_16x16x32_bf16 v[64:67], v[224:227], v[208:211], v[64:67]
	s_mov_b32 m0, s30
	v_lshl_add_u64 v[230:231], s[24:25], 0, v[128:129]
	s_barrier
	ds_read_b128 v[156:159], v189 offset:16384
	ds_read_b128 v[160:163], v189 offset:17408
	ds_read_b128 v[164:167], v189 offset:18432
	ds_read_b128 v[168:171], v189 offset:19456
	ds_read_b128 v[190:193], v189 offset:20480
	ds_read_b128 v[194:197], v189 offset:21504
	ds_read_b128 v[198:201], v189 offset:22528
	ds_read_b128 v[208:211], v189 offset:23552
	global_load_lds_dwordx4 v[230:231], off
	v_lshl_add_u64 v[232:233], s[24:25], 0, v[132:133]
	s_mov_b32 m0, s31
	s_nop 0
	global_load_lds_dwordx4 v[232:233], off
	s_barrier
	s_waitcnt lgkmcnt(0)
	v_mfma_f32_16x16x32_bf16 v[60:63], v[140:143], v[156:159], v[60:63]
	v_mfma_f32_16x16x32_bf16 v[56:59], v[148:151], v[156:159], v[56:59]
	v_mfma_f32_16x16x32_bf16 v[44:47], v[140:143], v[164:167], v[44:47]
	v_mfma_f32_16x16x32_bf16 v[40:43], v[148:151], v[164:167], v[40:43]
	v_mfma_f32_16x16x32_bf16 v[28:31], v[140:143], v[190:193], v[28:31]
	v_mfma_f32_16x16x32_bf16 v[24:27], v[148:151], v[190:193], v[24:27]
	v_mfma_f32_16x16x32_bf16 v[12:15], v[140:143], v[198:201], v[12:15]
	v_mfma_f32_16x16x32_bf16 v[8:11], v[148:151], v[198:201], v[8:11]
	v_mfma_f32_16x16x32_bf16 v[60:63], v[144:147], v[160:163], v[60:63]
	v_mfma_f32_16x16x32_bf16 v[56:59], v[152:155], v[160:163], v[56:59]
	v_mfma_f32_16x16x32_bf16 v[44:47], v[144:147], v[168:171], v[44:47]
	v_mfma_f32_16x16x32_bf16 v[40:43], v[152:155], v[168:171], v[40:43]
	v_mfma_f32_16x16x32_bf16 v[28:31], v[144:147], v[194:197], v[28:31]
	v_mfma_f32_16x16x32_bf16 v[24:27], v[152:155], v[194:197], v[24:27]
	v_mfma_f32_16x16x32_bf16 v[12:15], v[144:147], v[208:211], v[12:15]
	v_mfma_f32_16x16x32_bf16 v[8:11], v[152:155], v[208:211], v[8:11]
	s_barrier
	s_add_u32 s56, s20, 0x80000
	s_addc_u32 s57, s21, 0
	s_add_i32 s34, s35, s28
	v_lshl_add_u64 v[140:141], s[56:57], 0, v[130:131]
	s_mov_b32 m0, s34
	s_nop 0
	global_load_lds_dwordx4 v[140:141], off
	v_lshl_add_u64 v[140:141], s[56:57], 0, v[134:135]
	s_add_i32 m0, s34, 0x2000
	s_nop 0
	global_load_lds_dwordx4 v[140:141], off
	s_waitcnt vmcnt(6)
	s_barrier
	v_mfma_f32_16x16x32_bf16 v[52:55], v[212:215], v[156:159], v[52:55]
	v_mfma_f32_16x16x32_bf16 v[48:51], v[220:223], v[156:159], v[48:51]
	v_mfma_f32_16x16x32_bf16 v[36:39], v[212:215], v[164:167], v[36:39]
	v_mfma_f32_16x16x32_bf16 v[32:35], v[220:223], v[164:167], v[32:35]
	v_mfma_f32_16x16x32_bf16 v[20:23], v[212:215], v[190:193], v[20:23]
	v_mfma_f32_16x16x32_bf16 v[16:19], v[220:223], v[190:193], v[16:19]
	v_mfma_f32_16x16x32_bf16 v[4:7], v[212:215], v[198:201], v[4:7]
	v_mfma_f32_16x16x32_bf16 v[0:3], v[220:223], v[198:201], v[0:3]
	v_mfma_f32_16x16x32_bf16 v[52:55], v[216:219], v[160:163], v[52:55]
	v_mfma_f32_16x16x32_bf16 v[48:51], v[224:227], v[160:163], v[48:51]
	v_mfma_f32_16x16x32_bf16 v[36:39], v[216:219], v[168:171], v[36:39]
	v_mfma_f32_16x16x32_bf16 v[32:35], v[224:227], v[168:171], v[32:35]
	v_mfma_f32_16x16x32_bf16 v[20:23], v[216:219], v[194:197], v[20:23]
	v_mfma_f32_16x16x32_bf16 v[16:19], v[224:227], v[194:197], v[16:19]
	v_mfma_f32_16x16x32_bf16 v[4:7], v[216:219], v[208:211], v[4:7]
	v_mfma_f32_16x16x32_bf16 v[0:3], v[224:227], v[208:211], v[0:3]
	s_add_i32 s34, 0, 0x18000
	v_add_u32_e32 v152, s34, v174
	s_barrier
	ds_read_b128 v[140:143], v152
	ds_read_b128 v[144:147], v152 offset:1024
	ds_read_b128 v[148:151], v152 offset:2048
	ds_read_b128 v[152:155], v152 offset:3072
	s_add_u32 s24, s24, 0x80000
	s_addc_u32 s25, s25, 0
	s_mov_b32 m0, s33
	v_lshl_add_u64 v[212:213], s[24:25], 0, v[128:129]
	ds_read_b128 v[156:159], v189 offset:32768
	ds_read_b128 v[160:163], v189 offset:33792
	ds_read_b128 v[164:167], v189 offset:34816
	ds_read_b128 v[168:171], v189 offset:35840
	ds_read_b128 v[190:193], v189 offset:36864
	ds_read_b128 v[194:197], v189 offset:37888
	ds_read_b128 v[198:201], v189 offset:38912
	ds_read_b128 v[208:211], v189 offset:39936
	global_load_lds_dwordx4 v[212:213], off
	v_lshl_add_u64 v[212:213], s[24:25], 0, v[132:133]
	s_mov_b32 m0, s37
	s_nop 0
	global_load_lds_dwordx4 v[212:213], off
	s_waitcnt lgkmcnt(8)
	s_barrier
	s_waitcnt lgkmcnt(0)
	v_mfma_f32_16x16x32_bf16 v[124:127], v[140:143], v[156:159], v[124:127]
	v_mfma_f32_16x16x32_bf16 v[120:123], v[148:151], v[156:159], v[120:123]
	v_mfma_f32_16x16x32_bf16 v[108:111], v[140:143], v[164:167], v[108:111]
	v_mfma_f32_16x16x32_bf16 v[104:107], v[148:151], v[164:167], v[104:107]
	v_mfma_f32_16x16x32_bf16 v[92:95], v[140:143], v[190:193], v[92:95]
	v_mfma_f32_16x16x32_bf16 v[88:91], v[148:151], v[190:193], v[88:91]
	v_mfma_f32_16x16x32_bf16 v[76:79], v[140:143], v[198:201], v[76:79]
	v_mfma_f32_16x16x32_bf16 v[72:75], v[148:151], v[198:201], v[72:75]
	v_mfma_f32_16x16x32_bf16 v[124:127], v[144:147], v[160:163], v[124:127]
	v_mfma_f32_16x16x32_bf16 v[120:123], v[152:155], v[160:163], v[120:123]
	v_mfma_f32_16x16x32_bf16 v[108:111], v[144:147], v[168:171], v[108:111]
	v_mfma_f32_16x16x32_bf16 v[104:107], v[152:155], v[168:171], v[104:107]
	v_mfma_f32_16x16x32_bf16 v[92:95], v[144:147], v[194:197], v[92:95]
	v_mfma_f32_16x16x32_bf16 v[88:91], v[152:155], v[194:197], v[88:91]
	v_mfma_f32_16x16x32_bf16 v[76:79], v[144:147], v[208:211], v[76:79]
	v_mfma_f32_16x16x32_bf16 v[72:75], v[152:155], v[208:211], v[72:75]
	s_barrier
	s_add_i32 s24, 0, 0x1c000
	s_add_i32 s25, s34, s28
	v_add_u32_e32 v176, s24, v174
	v_lshl_add_u64 v[180:181], v[180:181], 0, s[40:41]
	s_mov_b32 m0, s25
	ds_read_b128 v[212:215], v176
	ds_read_b128 v[216:219], v176 offset:1024
	ds_read_b128 v[220:223], v176 offset:2048
	ds_read_b128 v[224:227], v176 offset:3072
	global_load_lds_dwordx4 v[180:181], off
	v_lshl_add_u64 v[180:181], v[228:229], 0, s[40:41]
	s_add_i32 m0, s25, 0x2000
	s_nop 0
	global_load_lds_dwordx4 v[180:181], off
	s_barrier
	s_waitcnt lgkmcnt(0)
	v_mfma_f32_16x16x32_bf16 v[116:119], v[212:215], v[156:159], v[116:119]
	v_mfma_f32_16x16x32_bf16 v[112:115], v[220:223], v[156:159], v[112:115]
	v_mfma_f32_16x16x32_bf16 v[100:103], v[212:215], v[164:167], v[100:103]
	v_mfma_f32_16x16x32_bf16 v[96:99], v[220:223], v[164:167], v[96:99]
	v_mfma_f32_16x16x32_bf16 v[84:87], v[212:215], v[190:193], v[84:87]
	v_mfma_f32_16x16x32_bf16 v[80:83], v[220:223], v[190:193], v[80:83]
	v_mfma_f32_16x16x32_bf16 v[68:71], v[212:215], v[198:201], v[68:71]
	v_mfma_f32_16x16x32_bf16 v[64:67], v[220:223], v[198:201], v[64:67]
	v_mfma_f32_16x16x32_bf16 v[116:119], v[216:219], v[160:163], v[116:119]
	v_mfma_f32_16x16x32_bf16 v[112:115], v[224:227], v[160:163], v[112:115]
	v_mfma_f32_16x16x32_bf16 v[100:103], v[216:219], v[168:171], v[100:103]
	v_mfma_f32_16x16x32_bf16 v[96:99], v[224:227], v[168:171], v[96:99]
	v_mfma_f32_16x16x32_bf16 v[84:87], v[216:219], v[194:197], v[84:87]
	v_mfma_f32_16x16x32_bf16 v[80:83], v[224:227], v[194:197], v[80:83]
	v_mfma_f32_16x16x32_bf16 v[68:71], v[216:219], v[208:211], v[68:71]
	v_mfma_f32_16x16x32_bf16 v[64:67], v[224:227], v[208:211], v[64:67]
	s_mov_b32 m0, s47
	v_lshl_add_u64 v[180:181], v[230:231], 0, s[40:41]
	s_barrier
	ds_read_b128 v[156:159], v189 offset:49152
	ds_read_b128 v[160:163], v189 offset:50176
	ds_read_b128 v[164:167], v189 offset:51200
	ds_read_b128 v[168:171], v189 offset:52224
	ds_read_b128 v[190:193], v189 offset:53248
	ds_read_b128 v[194:197], v189 offset:54272
	ds_read_b128 v[198:201], v189 offset:55296
	ds_read_b128 v[208:211], v189 offset:56320
	global_load_lds_dwordx4 v[180:181], off
	v_lshl_add_u64 v[180:181], v[232:233], 0, s[40:41]
	s_mov_b32 m0, s48
	s_nop 0
	global_load_lds_dwordx4 v[180:181], off
	s_barrier
	s_waitcnt lgkmcnt(0)
	v_mfma_f32_16x16x32_bf16 v[60:63], v[140:143], v[156:159], v[60:63]
	v_mfma_f32_16x16x32_bf16 v[56:59], v[148:151], v[156:159], v[56:59]
	v_mfma_f32_16x16x32_bf16 v[44:47], v[140:143], v[164:167], v[44:47]
	v_mfma_f32_16x16x32_bf16 v[40:43], v[148:151], v[164:167], v[40:43]
	v_mfma_f32_16x16x32_bf16 v[28:31], v[140:143], v[190:193], v[28:31]
	v_mfma_f32_16x16x32_bf16 v[24:27], v[148:151], v[190:193], v[24:27]
	v_mfma_f32_16x16x32_bf16 v[12:15], v[140:143], v[198:201], v[12:15]
	v_mfma_f32_16x16x32_bf16 v[8:11], v[148:151], v[198:201], v[8:11]
	v_mfma_f32_16x16x32_bf16 v[60:63], v[144:147], v[160:163], v[60:63]
	v_mfma_f32_16x16x32_bf16 v[56:59], v[152:155], v[160:163], v[56:59]
	v_mfma_f32_16x16x32_bf16 v[44:47], v[144:147], v[168:171], v[44:47]
	v_mfma_f32_16x16x32_bf16 v[40:43], v[152:155], v[168:171], v[40:43]
	v_mfma_f32_16x16x32_bf16 v[28:31], v[144:147], v[194:197], v[28:31]
	v_mfma_f32_16x16x32_bf16 v[24:27], v[152:155], v[194:197], v[24:27]
	v_mfma_f32_16x16x32_bf16 v[12:15], v[144:147], v[208:211], v[12:15]
	v_mfma_f32_16x16x32_bf16 v[8:11], v[152:155], v[208:211], v[8:11]
	s_barrier
	s_add_u32 s20, s20, 0x80080
	s_addc_u32 s21, s21, 0
	s_add_i32 s24, s24, s28
	v_lshl_add_u64 v[140:141], s[20:21], 0, v[130:131]
	s_mov_b32 m0, s24
	s_nop 0
	global_load_lds_dwordx4 v[140:141], off
	v_lshl_add_u64 v[140:141], s[20:21], 0, v[134:135]
	s_add_i32 m0, s24, 0x2000
	s_nop 0
	global_load_lds_dwordx4 v[140:141], off
	s_waitcnt vmcnt(6)
	s_barrier
	v_mfma_f32_16x16x32_bf16 v[52:55], v[212:215], v[156:159], v[52:55]
	v_mfma_f32_16x16x32_bf16 v[48:51], v[220:223], v[156:159], v[48:51]
	v_mfma_f32_16x16x32_bf16 v[36:39], v[212:215], v[164:167], v[36:39]
	v_mfma_f32_16x16x32_bf16 v[32:35], v[220:223], v[164:167], v[32:35]
	v_mfma_f32_16x16x32_bf16 v[20:23], v[212:215], v[190:193], v[20:23]
	v_mfma_f32_16x16x32_bf16 v[16:19], v[220:223], v[190:193], v[16:19]
	v_mfma_f32_16x16x32_bf16 v[4:7], v[212:215], v[198:201], v[4:7]
	v_mfma_f32_16x16x32_bf16 v[0:3], v[220:223], v[198:201], v[0:3]
	v_mfma_f32_16x16x32_bf16 v[52:55], v[216:219], v[160:163], v[52:55]
	v_mfma_f32_16x16x32_bf16 v[48:51], v[224:227], v[160:163], v[48:51]
	v_mfma_f32_16x16x32_bf16 v[36:39], v[216:219], v[168:171], v[36:39]
	v_mfma_f32_16x16x32_bf16 v[32:35], v[224:227], v[168:171], v[32:35]
	v_mfma_f32_16x16x32_bf16 v[20:23], v[216:219], v[194:197], v[20:23]
	v_mfma_f32_16x16x32_bf16 v[16:19], v[224:227], v[194:197], v[16:19]
	v_mfma_f32_16x16x32_bf16 v[4:7], v[216:219], v[208:211], v[4:7]
	v_mfma_f32_16x16x32_bf16 v[0:3], v[224:227], v[208:211], v[0:3]
	s_add_i32 s54, s54, 2
	s_add_u32 s44, s44, 0x100
	s_addc_u32 s53, s53, 0
	s_add_u32 s18, s18, 0x100
	s_addc_u32 s19, s19, 0
	s_cmp_gt_u32 s54, 29
	s_barrier
	s_cbranch_scc0 .LBB0_656
	s_lshl_b32 s5, s16, 8
	s_cmp_lt_i32 s14, 18
	v_readlane_b32 s20, v255, 32
	s_cselect_b64 s[18:19], -1, 0
	v_readlane_b32 s21, v255, 33
	s_or_b64 s[20:21], s[20:21], s[18:19]
	s_mov_b64 s[18:19], -1
	s_and_b64 vcc, exec, s[20:21]
	v_mov_b32_e32 v198, 0xbf1f24be
	s_cbranch_vccnz .LBB0_664
	s_sub_i32 s9, s14, 18
	s_cmp_gt_i32 s16, 31
	s_cbranch_scc0 .LBB0_660
	s_sub_i32 s15, s16, 32
	s_lshr_b32 s15, s15, 1
	s_and_b32 s15, s15, 0x1fffffc
	s_add_i32 s15, s15, s9
	s_lshl_b32 s44, s15, 7
	s_lshl_b64 s[18:19], s[44:45], 13
	s_add_u32 s24, s38, s18
	s_addc_u32 s25, s39, s19
	s_and_b32 s15, s5, 0x700
	s_add_i32 s15, s15, s46
	s_mov_b64 s[18:19], 0
